# epilogue rs loads hoisted + counted waits, first-iteration vmcnt skip, barrier early L1 invalidate + cached coloc flag
# speedup vs baseline: 1.0239x; 1.0239x over previous
; #define PG8_STAGE(bufoff, gbase, voff) do { _Pragma("unroll") for (int _i = 0; _i < 2; ++_i) \
;         __builtin_amdgcn_global_load_lds((const unsigned*)((const char*)(gbase) + (voff)[_i]), (PG8_LAS unsigned*)(lds + (bufoff) + ldsw + _i * 8192), 16, 0, 0); } while (0)
; #define PG8_LDA(dst, b, h) do { _Pragma("unroll") for (int m = 0; m < 4; ++m) _Pragma("unroll") for (int k = 0; k < 2; ++k) dst[m][k] = *(const PG8_LAS bf16x8*)(lds + PG8_SA(b, h) + aoff + m * 2048 + k * 1024); } while (0)
; #define PG8_LDB(dst, b, h) do { _Pragma("unroll") for (int n = 0; n < 2; ++n) _Pragma("unroll") for (int k = 0; k < 2; ++k) dst[n][k] = *(const PG8_LAS bf16x8*)(lds + PG8_SB(b, h) + boff + n * 2048 + k * 1024); } while (0)
; #define PG8_MMA(ai, bj, At, Bt) do { __builtin_amdgcn_s_setprio(1); _Pragma("unroll") for (int m = 0; m < 4; ++m) _Pragma("unroll") for (int n = 0; n < 2; ++n) _Pragma("unroll") for (int k = 0; k < 2; ++k) \
;         acc[ai][bj][m][n] = __builtin_amdgcn_mfma_f32_16x16x32_bf16(Bt[n][k], At[m][k], acc[ai][bj][m][n], 0, 0, 0); __builtin_amdgcn_s_setprio(0); } while (0)
; #define PG8_WAIT_V(n) asm volatile("s_waitcnt vmcnt(" #n ")" ::: "memory")
; #define PG8_BAR __builtin_amdgcn_s_barrier()
; template <class Epi, class Sched, bool ALIGN_EPI = false, bool SP2 = false>
; __device__ __forceinline__ void gemm_phase(PG8_LAS unsigned char* lds, const Gemm g, const Sched& S, const Epi& E, const int tid) {
;     ...
;         for (int t = 0; t < nt; t += 2) {
;             const bool last = (t == nt - 2);
;             const char* a1 = cA + (size_t)(t + 1) * kstep;
;             const char* a2 = last ? nA : cA + (size_t)(t + 2) * kstep; const char* b2 = last ? nB : cB + (size_t)(t + 2) * kstep;
;             const char* a3 = a2 + kstep; const char* b3 = b2 + kstep;
;             if (last && has_next) S.a_ready(nxt);
;             if constexpr (SP2) {
;             PG8_LDB(B0, 0, 0); PG8_LDB(B1, 0, 1); PG8_SCHED; PG8_LDA(At, 0, 0); PG8_STAGE(PG8_SA(1, 1), a1 + hstepA, voffA);
;             PG8_WAIT_V(8); PG8_WAIT_L(0); PG8_BAR; PG8_MMA(0, 0, At, B0); PG8_MMA(0, 1, At, B1); PG8_BAR; PG8_SCHED;
;             PG8_LDA(At, 0, 1); PG8_STAGE(PG8_SB(0, 0), b2, voffB); PG8_STAGE(PG8_SB(0, 1), b2 + hstepB, voffB); PG8_STAGE(PG8_SA(0, 0), a2, voffA);
;             PG8_WAIT_V(8); PG8_WAIT_L(0); PG8_BAR; PG8_MMA(1, 0, At, B0); PG8_MMA(1, 1, At, B1); PG8_BAR; PG8_SCHED;
.LBB0_35:
	s_add_u32 s18, s8, 0xfff80080
	s_addc_u32 s19, s9, -1
	s_add_i32 s36, 0, 0x10000
	s_cmp_eq_u32 s31, 12
	s_cselect_b32 s23, s26, s19
	s_cselect_b32 s22, s27, s18
	v_add_u32_e32 v128, s36, v155
	s_cselect_b32 s19, s13, s30
	s_cselect_b32 s18, s28, s29
	s_cmp_eq_u32 s31, -2
	s_cselect_b32 s99, 1, 0
	s_cmp_eq_u32 s89, 1
	s_cselect_b32 s99, 0, s99
	s_add_i32 s38, 0, 0x14000
	ds_read_b128 v[148:151], v128
	ds_read_b128 v[158:161], v128 offset:1024
	ds_read_b128 v[162:165], v128 offset:2048
	ds_read_b128 v[188:191], v128 offset:3072
	v_add_u32_e32 v128, s38, v155
	ds_read_b128 v[192:195], v128
	ds_read_b128 v[196:199], v128 offset:1024
	ds_read_b128 v[200:203], v128 offset:2048
	ds_read_b128 v[204:207], v128 offset:3072
	v_lshl_add_u64 v[166:167], s[8:9], 0, v[144:145]
	s_add_i32 m0, s69, 0xc000
	ds_read_b128 v[208:211], v157
	ds_read_b128 v[212:215], v157 offset:1024
	ds_read_b128 v[216:219], v157 offset:2048
	ds_read_b128 v[220:223], v157 offset:3072
	ds_read_b128 v[224:227], v157 offset:4096
	ds_read_b128 v[228:231], v157 offset:5120
	ds_read_b128 v[232:235], v157 offset:6144
	ds_read_b128 v[236:239], v157 offset:7168
	global_load_lds_dwordx4 v[166:167], off
	v_lshl_add_u64 v[166:167], s[8:9], 0, v[146:147]
	s_add_i32 m0, s69, 0xe000
	s_nop 0
	global_load_lds_dwordx4 v[166:167], off
	s_cmp_eq_u32 s99, 1
	s_cbranch_scc1 .Lkw_up_0
	s_waitcnt vmcnt(8)
.Lkw_up_0:
	s_waitcnt lgkmcnt(0)
	s_barrier
	s_setprio 1
	s_waitcnt lgkmcnt(0)
	v_mfma_f32_16x16x32_bf16 v[124:127], v[148:151], v[208:211], v[124:127]
	v_mfma_f32_16x16x32_bf16 v[120:123], v[162:165], v[208:211], v[120:123]
	v_mfma_f32_16x16x32_bf16 v[108:111], v[148:151], v[216:219], v[108:111]
	v_mfma_f32_16x16x32_bf16 v[104:107], v[162:165], v[216:219], v[104:107]
	v_mfma_f32_16x16x32_bf16 v[92:95], v[148:151], v[224:227], v[92:95]
	v_mfma_f32_16x16x32_bf16 v[88:91], v[162:165], v[224:227], v[88:91]
	v_mfma_f32_16x16x32_bf16 v[76:79], v[148:151], v[232:235], v[76:79]
	v_mfma_f32_16x16x32_bf16 v[72:75], v[162:165], v[232:235], v[72:75]
	v_mfma_f32_16x16x32_bf16 v[124:127], v[158:161], v[212:215], v[124:127]
	v_mfma_f32_16x16x32_bf16 v[120:123], v[188:191], v[212:215], v[120:123]
	v_mfma_f32_16x16x32_bf16 v[108:111], v[158:161], v[220:223], v[108:111]
	v_mfma_f32_16x16x32_bf16 v[104:107], v[188:191], v[220:223], v[104:107]
	v_mfma_f32_16x16x32_bf16 v[92:95], v[158:161], v[228:231], v[92:95]
	v_mfma_f32_16x16x32_bf16 v[88:91], v[188:191], v[228:231], v[88:91]
	v_mfma_f32_16x16x32_bf16 v[76:79], v[158:161], v[236:239], v[76:79]
	v_mfma_f32_16x16x32_bf16 v[72:75], v[188:191], v[236:239], v[72:75]
	s_setprio 0
	s_setprio 1
	v_mfma_f32_16x16x32_bf16 v[116:119], v[192:195], v[208:211], v[116:119]
	v_mfma_f32_16x16x32_bf16 v[112:115], v[200:203], v[208:211], v[112:115]
	v_mfma_f32_16x16x32_bf16 v[100:103], v[192:195], v[216:219], v[100:103]
	v_mfma_f32_16x16x32_bf16 v[96:99], v[200:203], v[216:219], v[96:99]
	v_mfma_f32_16x16x32_bf16 v[84:87], v[192:195], v[224:227], v[84:87]
	v_mfma_f32_16x16x32_bf16 v[80:83], v[200:203], v[224:227], v[80:83]
	v_mfma_f32_16x16x32_bf16 v[68:71], v[192:195], v[232:235], v[68:71]
	v_mfma_f32_16x16x32_bf16 v[64:67], v[200:203], v[232:235], v[64:67]
	v_mfma_f32_16x16x32_bf16 v[116:119], v[196:199], v[212:215], v[116:119]
	v_mfma_f32_16x16x32_bf16 v[112:115], v[204:207], v[212:215], v[112:115]
	v_mfma_f32_16x16x32_bf16 v[100:103], v[196:199], v[220:223], v[100:103]
	v_mfma_f32_16x16x32_bf16 v[96:99], v[204:207], v[220:223], v[96:99]
	v_mfma_f32_16x16x32_bf16 v[84:87], v[196:199], v[228:231], v[84:87]
	v_mfma_f32_16x16x32_bf16 v[80:83], v[204:207], v[228:231], v[80:83]
	v_mfma_f32_16x16x32_bf16 v[68:71], v[196:199], v[236:239], v[68:71]
	v_mfma_f32_16x16x32_bf16 v[64:67], v[204:207], v[236:239], v[64:67]
	s_setprio 0
	s_barrier
	s_add_i32 s36, s36, s68
	v_lshl_add_u64 v[166:167], s[18:19], 0, v[140:141]
	s_mov_b32 m0, s36
	ds_read_b128 v[208:211], v157 offset:16384
	ds_read_b128 v[212:215], v157 offset:17408
	ds_read_b128 v[216:219], v157 offset:18432
	ds_read_b128 v[220:223], v157 offset:19456
	ds_read_b128 v[224:227], v157 offset:20480
	ds_read_b128 v[228:231], v157 offset:21504
	ds_read_b128 v[232:235], v157 offset:22528
	ds_read_b128 v[236:239], v157 offset:23552
	global_load_lds_dwordx4 v[166:167], off
	s_add_i32 m0, s36, 0x2000
	s_add_u32 s36, s18, 0x40000
	v_lshl_add_u64 v[240:241], s[18:19], 0, v[136:137]
	s_addc_u32 s37, s19, 0
	s_add_i32 s38, s38, s68
	global_load_lds_dwordx4 v[240:241], off
	v_lshl_add_u64 v[242:243], s[36:37], 0, v[140:141]
	s_mov_b32 m0, s38
	v_lshl_add_u64 v[244:245], s[22:23], 0, v[138:139]
	global_load_lds_dwordx4 v[242:243], off
	v_lshl_add_u64 v[242:243], s[36:37], 0, v[136:137]
	s_add_i32 m0, s38, 0x2000
	s_nop 0
	global_load_lds_dwordx4 v[242:243], off
	v_lshl_add_u64 v[242:243], s[22:23], 0, v[142:143]
	s_mov_b32 m0, s69
	s_nop 0
	global_load_lds_dwordx4 v[242:243], off
	s_mov_b32 m0, s70
	s_nop 0
	global_load_lds_dwordx4 v[244:245], off
	s_cmp_eq_u32 s99, 1
	s_cbranch_scc1 .Lkw_up_1
	s_waitcnt vmcnt(8)
; #define PG8_STAGE(bufoff, gbase, voff) do { _Pragma("unroll") for (int _i = 0; _i < 2; ++_i) \
;         __builtin_amdgcn_global_load_lds((const unsigned*)((const char*)(gbase) + (voff)[_i]), (PG8_LAS unsigned*)(lds + (bufoff) + ldsw + _i * 8192), 16, 0, 0); } while (0)
; #define PG8_LDA(dst, b, h) do { _Pragma("unroll") for (int m = 0; m < 4; ++m) _Pragma("unroll") for (int k = 0; k < 2; ++k) dst[m][k] = *(const PG8_LAS bf16x8*)(lds + PG8_SA(b, h) + aoff + m * 2048 + k * 1024); } while (0)
; #define PG8_LDB(dst, b, h) do { _Pragma("unroll") for (int n = 0; n < 2; ++n) _Pragma("unroll") for (int k = 0; k < 2; ++k) dst[n][k] = *(const PG8_LAS bf16x8*)(lds + PG8_SB(b, h) + boff + n * 2048 + k * 1024); } while (0)
; #define PG8_MMA(ai, bj, At, Bt) do { __builtin_amdgcn_s_setprio(1); _Pragma("unroll") for (int m = 0; m < 4; ++m) _Pragma("unroll") for (int n = 0; n < 2; ++n) _Pragma("unroll") for (int k = 0; k < 2; ++k) \
;         acc[ai][bj][m][n] = __builtin_amdgcn_mfma_f32_16x16x32_bf16(Bt[n][k], At[m][k], acc[ai][bj][m][n], 0, 0, 0); __builtin_amdgcn_s_setprio(0); } while (0)
; #define PG8_WAIT_V(n) asm volatile("s_waitcnt vmcnt(" #n ")" ::: "memory")
; #define PG8_WAIT_L(n) asm volatile("s_waitcnt lgkmcnt(" #n ")" ::: "memory")
; #define PG8_BAR __builtin_amdgcn_s_barrier()
; #define PG8_SCHED __builtin_amdgcn_sched_barrier(0)
; template <class Epi, class Sched, bool ALIGN_EPI = false, bool SP2 = false>
; __device__ __forceinline__ void gemm_phase(PG8_LAS unsigned char* lds, const Gemm g, const Sched& S, const Epi& E, const int tid) {
;     ...
;             PG8_WAIT_V(8); PG8_WAIT_L(0); PG8_BAR; PG8_MMA(0, 0, At, B0); PG8_MMA(0, 1, At, B1); PG8_BAR; PG8_SCHED;
;             PG8_LDA(At, 0, 1); PG8_STAGE(PG8_SB(0, 0), b2, voffB); PG8_STAGE(PG8_SB(0, 1), b2 + hstepB, voffB); PG8_STAGE(PG8_SA(0, 0), a2, voffA);
;             PG8_WAIT_V(8); PG8_WAIT_L(0); PG8_BAR; PG8_MMA(1, 0, At, B0); PG8_MMA(1, 1, At, B1); PG8_BAR; PG8_SCHED;
;             PG8_LDB(B0, 1, 0); PG8_LDB(B1, 1, 1); PG8_SCHED; PG8_LDA(At, 1, 0); PG8_STAGE(PG8_SA(0, 1), a2 + hstepA, voffA);
;             PG8_WAIT_V(8); PG8_WAIT_L(0); PG8_BAR; PG8_MMA(0, 0, At, B0); PG8_MMA(0, 1, At, B1); PG8_BAR; PG8_SCHED;
.Lkw_up_1:
	s_waitcnt lgkmcnt(0)
	s_barrier
	s_setprio 1
	s_waitcnt lgkmcnt(0)
	v_mfma_f32_16x16x32_bf16 v[60:63], v[148:151], v[208:211], v[60:63]
	v_mfma_f32_16x16x32_bf16 v[56:59], v[162:165], v[208:211], v[56:59]
	v_mfma_f32_16x16x32_bf16 v[44:47], v[148:151], v[216:219], v[44:47]
	v_mfma_f32_16x16x32_bf16 v[40:43], v[162:165], v[216:219], v[40:43]
	v_mfma_f32_16x16x32_bf16 v[28:31], v[148:151], v[224:227], v[28:31]
	v_mfma_f32_16x16x32_bf16 v[24:27], v[162:165], v[224:227], v[24:27]
	v_mfma_f32_16x16x32_bf16 v[12:15], v[148:151], v[232:235], v[12:15]
	v_mfma_f32_16x16x32_bf16 v[8:11], v[162:165], v[232:235], v[8:11]
	v_mfma_f32_16x16x32_bf16 v[60:63], v[158:161], v[212:215], v[60:63]
	v_mfma_f32_16x16x32_bf16 v[56:59], v[188:191], v[212:215], v[56:59]
	v_mfma_f32_16x16x32_bf16 v[44:47], v[158:161], v[220:223], v[44:47]
	v_mfma_f32_16x16x32_bf16 v[40:43], v[188:191], v[220:223], v[40:43]
	v_mfma_f32_16x16x32_bf16 v[28:31], v[158:161], v[228:231], v[28:31]
	v_mfma_f32_16x16x32_bf16 v[24:27], v[188:191], v[228:231], v[24:27]
	v_mfma_f32_16x16x32_bf16 v[12:15], v[158:161], v[236:239], v[12:15]
	v_mfma_f32_16x16x32_bf16 v[8:11], v[188:191], v[236:239], v[8:11]
	s_setprio 0
	s_setprio 1
	v_mfma_f32_16x16x32_bf16 v[52:55], v[192:195], v[208:211], v[52:55]
	v_mfma_f32_16x16x32_bf16 v[48:51], v[200:203], v[208:211], v[48:51]
	v_mfma_f32_16x16x32_bf16 v[36:39], v[192:195], v[216:219], v[36:39]
	v_mfma_f32_16x16x32_bf16 v[32:35], v[200:203], v[216:219], v[32:35]
	v_mfma_f32_16x16x32_bf16 v[20:23], v[192:195], v[224:227], v[20:23]
	v_mfma_f32_16x16x32_bf16 v[16:19], v[200:203], v[224:227], v[16:19]
	v_mfma_f32_16x16x32_bf16 v[4:7], v[192:195], v[232:235], v[4:7]
	v_mfma_f32_16x16x32_bf16 v[0:3], v[200:203], v[232:235], v[0:3]
	v_mfma_f32_16x16x32_bf16 v[52:55], v[196:199], v[212:215], v[52:55]
	v_mfma_f32_16x16x32_bf16 v[48:51], v[204:207], v[212:215], v[48:51]
	v_mfma_f32_16x16x32_bf16 v[36:39], v[196:199], v[220:223], v[36:39]
	v_mfma_f32_16x16x32_bf16 v[32:35], v[204:207], v[220:223], v[32:35]
	v_mfma_f32_16x16x32_bf16 v[20:23], v[196:199], v[228:231], v[20:23]
	v_mfma_f32_16x16x32_bf16 v[16:19], v[204:207], v[228:231], v[16:19]
	v_mfma_f32_16x16x32_bf16 v[4:7], v[196:199], v[236:239], v[4:7]
	v_mfma_f32_16x16x32_bf16 v[0:3], v[204:207], v[236:239], v[0:3]
	s_setprio 0
	s_barrier
	s_add_i32 s36, 0, 0x18000
	v_add_u32_e32 v128, s36, v155
	s_add_i32 s37, 0, 0x1c000
	ds_read_b128 v[148:151], v128
	ds_read_b128 v[158:161], v128 offset:1024
	ds_read_b128 v[162:165], v128 offset:2048
	ds_read_b128 v[188:191], v128 offset:3072
	v_add_u32_e32 v128, s37, v155
	ds_read_b128 v[192:195], v128
	ds_read_b128 v[196:199], v128 offset:1024
	ds_read_b128 v[200:203], v128 offset:2048
	ds_read_b128 v[204:207], v128 offset:3072
	s_add_u32 s22, s22, 0x80000
	s_addc_u32 s23, s23, 0
	s_mov_b32 m0, s71
	v_lshl_add_u64 v[246:247], s[22:23], 0, v[142:143]
	ds_read_b128 v[208:211], v157 offset:32768
	ds_read_b128 v[212:215], v157 offset:33792
	ds_read_b128 v[216:219], v157 offset:34816
	ds_read_b128 v[220:223], v157 offset:35840
	ds_read_b128 v[224:227], v157 offset:36864
	ds_read_b128 v[228:231], v157 offset:37888
	ds_read_b128 v[232:235], v157 offset:38912
	ds_read_b128 v[236:239], v157 offset:39936
	global_load_lds_dwordx4 v[246:247], off
	v_lshl_add_u64 v[246:247], s[22:23], 0, v[138:139]
	s_mov_b32 m0, s74
	s_nop 0
	global_load_lds_dwordx4 v[246:247], off
	s_waitcnt vmcnt(8)
	s_waitcnt lgkmcnt(0)
	s_barrier
	s_setprio 1
	s_waitcnt lgkmcnt(0)
	v_mfma_f32_16x16x32_bf16 v[124:127], v[148:151], v[208:211], v[124:127]
	v_mfma_f32_16x16x32_bf16 v[120:123], v[162:165], v[208:211], v[120:123]
	v_mfma_f32_16x16x32_bf16 v[108:111], v[148:151], v[216:219], v[108:111]
	v_mfma_f32_16x16x32_bf16 v[104:107], v[162:165], v[216:219], v[104:107]
	v_mfma_f32_16x16x32_bf16 v[92:95], v[148:151], v[224:227], v[92:95]
	v_mfma_f32_16x16x32_bf16 v[88:91], v[162:165], v[224:227], v[88:91]
	v_mfma_f32_16x16x32_bf16 v[76:79], v[148:151], v[232:235], v[76:79]
	v_mfma_f32_16x16x32_bf16 v[72:75], v[162:165], v[232:235], v[72:75]
	v_mfma_f32_16x16x32_bf16 v[124:127], v[158:161], v[212:215], v[124:127]
	v_mfma_f32_16x16x32_bf16 v[120:123], v[188:191], v[212:215], v[120:123]
	v_mfma_f32_16x16x32_bf16 v[108:111], v[158:161], v[220:223], v[108:111]
	v_mfma_f32_16x16x32_bf16 v[104:107], v[188:191], v[220:223], v[104:107]
	v_mfma_f32_16x16x32_bf16 v[92:95], v[158:161], v[228:231], v[92:95]
	v_mfma_f32_16x16x32_bf16 v[88:91], v[188:191], v[228:231], v[88:91]
	v_mfma_f32_16x16x32_bf16 v[76:79], v[158:161], v[236:239], v[76:79]
	v_mfma_f32_16x16x32_bf16 v[72:75], v[188:191], v[236:239], v[72:75]
	s_setprio 0
	s_setprio 1
	v_mfma_f32_16x16x32_bf16 v[116:119], v[192:195], v[208:211], v[116:119]
	v_mfma_f32_16x16x32_bf16 v[112:115], v[200:203], v[208:211], v[112:115]
	v_mfma_f32_16x16x32_bf16 v[100:103], v[192:195], v[216:219], v[100:103]
	v_mfma_f32_16x16x32_bf16 v[96:99], v[200:203], v[216:219], v[96:99]
	v_mfma_f32_16x16x32_bf16 v[84:87], v[192:195], v[224:227], v[84:87]
	v_mfma_f32_16x16x32_bf16 v[80:83], v[200:203], v[224:227], v[80:83]
	v_mfma_f32_16x16x32_bf16 v[68:71], v[192:195], v[232:235], v[68:71]
	v_mfma_f32_16x16x32_bf16 v[64:67], v[200:203], v[232:235], v[64:67]
	v_mfma_f32_16x16x32_bf16 v[116:119], v[196:199], v[212:215], v[116:119]
	v_mfma_f32_16x16x32_bf16 v[112:115], v[204:207], v[212:215], v[112:115]
	v_mfma_f32_16x16x32_bf16 v[100:103], v[196:199], v[220:223], v[100:103]
	v_mfma_f32_16x16x32_bf16 v[96:99], v[204:207], v[220:223], v[96:99]
	v_mfma_f32_16x16x32_bf16 v[84:87], v[196:199], v[228:231], v[84:87]
	v_mfma_f32_16x16x32_bf16 v[80:83], v[204:207], v[228:231], v[80:83]
	v_mfma_f32_16x16x32_bf16 v[68:71], v[196:199], v[236:239], v[68:71]
	v_mfma_f32_16x16x32_bf16 v[64:67], v[204:207], v[236:239], v[64:67]
	s_setprio 0
	s_barrier
; #define PG8_STAGE(bufoff, gbase, voff) do { _Pragma("unroll") for (int _i = 0; _i < 2; ++_i) \
;         __builtin_amdgcn_global_load_lds((const unsigned*)((const char*)(gbase) + (voff)[_i]), (PG8_LAS unsigned*)(lds + (bufoff) + ldsw + _i * 8192), 16, 0, 0); } while (0)
; #define PG8_LDA(dst, b, h) do { _Pragma("unroll") for (int m = 0; m < 4; ++m) _Pragma("unroll") for (int k = 0; k < 2; ++k) dst[m][k] = *(const PG8_LAS bf16x8*)(lds + PG8_SA(b, h) + aoff + m * 2048 + k * 1024); } while (0)
; #define PG8_MMA(ai, bj, At, Bt) do { __builtin_amdgcn_s_setprio(1); _Pragma("unroll") for (int m = 0; m < 4; ++m) _Pragma("unroll") for (int n = 0; n < 2; ++n) _Pragma("unroll") for (int k = 0; k < 2; ++k) \
;         acc[ai][bj][m][n] = __builtin_amdgcn_mfma_f32_16x16x32_bf16(Bt[n][k], At[m][k], acc[ai][bj][m][n], 0, 0, 0); __builtin_amdgcn_s_setprio(0); } while (0)
; #define PG8_WAIT_V(n) asm volatile("s_waitcnt vmcnt(" #n ")" ::: "memory")
; #define PG8_WAIT_L(n) asm volatile("s_waitcnt lgkmcnt(" #n ")" ::: "memory")
; #define PG8_BAR __builtin_amdgcn_s_barrier()
; #define PG8_SCHED __builtin_amdgcn_sched_barrier(0)
;     __device__ __forceinline__ void operator()(const f32x4 (&acc)[2][2][4][2], const Unit& u, int wr, int wc, int fr, int fq) const {
;         const int row0 = u.pm * BM + wr * 64 + fr; const int col0 = u.pn * BM + wc * 32 + 8 * fq;
; #pragma unroll
;         for (int ai = 0; ai < 2; ++ai)
; #pragma unroll
;             for (int m = 0; m < 4; ++m) { const int row_ = row0 + ai * HALF + m * 16; bf16_t* rowp = O + (size_t)(row_ >> 11) * gs + (size_t)(row_ & 2047) * ldc + col0; const float sc = rs ? rs[row0 + ai * HALF + m * 16] : 1.f;
; template <class Epi, class Sched, bool ALIGN_EPI = false, bool SP2 = false>
; __device__ __forceinline__ void gemm_phase(PG8_LAS unsigned char* lds, const Gemm g, const Sched& S, const Epi& E, const int tid) {
;     ...
;             PG8_WAIT_V(8); PG8_WAIT_L(0); PG8_BAR; PG8_MMA(0, 0, At, B0); PG8_MMA(0, 1, At, B1); PG8_BAR; PG8_SCHED;
;             PG8_LDA(At, 1, 1); PG8_STAGE(PG8_SB(1, 0), b3, voffB); PG8_STAGE(PG8_SB(1, 1), b3 + hstepB, voffB); PG8_STAGE(PG8_SA(1, 0), a3, voffA);
;             PG8_WAIT_V(8); PG8_WAIT_L(0); PG8_BAR; PG8_MMA(1, 0, At, B0); PG8_MMA(1, 1, At, B1); PG8_BAR; PG8_SCHED;
	s_add_i32 s22, s36, s68
	v_lshl_add_u64 v[166:167], v[166:167], 0, s[76:77]
	s_mov_b32 m0, s22
	ds_read_b128 v[208:211], v157 offset:49152
	ds_read_b128 v[212:215], v157 offset:50176
	ds_read_b128 v[216:219], v157 offset:51200
	ds_read_b128 v[220:223], v157 offset:52224
	ds_read_b128 v[224:227], v157 offset:53248
	ds_read_b128 v[228:231], v157 offset:54272
	ds_read_b128 v[232:235], v157 offset:55296
	ds_read_b128 v[236:239], v157 offset:56320
	global_load_lds_dwordx4 v[166:167], off
	s_add_i32 m0, s22, 0x2000
	s_add_u32 s18, s18, 0x40080
	v_lshl_add_u64 v[166:167], v[240:241], 0, s[76:77]
	s_addc_u32 s19, s19, 0
	s_add_i32 s22, s37, s68
	global_load_lds_dwordx4 v[166:167], off
	v_lshl_add_u64 v[166:167], s[18:19], 0, v[140:141]
	s_mov_b32 m0, s22
	s_nop 0
	global_load_lds_dwordx4 v[166:167], off
	v_lshl_add_u64 v[166:167], s[18:19], 0, v[136:137]
	s_add_i32 m0, s22, 0x2000
	s_nop 0
	global_load_lds_dwordx4 v[166:167], off
	v_lshl_add_u64 v[166:167], v[242:243], 0, s[76:77]
	s_mov_b32 m0, s84
	s_nop 0
	global_load_lds_dwordx4 v[166:167], off
	v_lshl_add_u64 v[166:167], v[244:245], 0, s[76:77]
	s_mov_b32 m0, s87
	s_nop 0
	global_load_lds_dwordx4 v[166:167], off
	s_waitcnt vmcnt(8)
	s_waitcnt lgkmcnt(0)
	s_barrier
	s_setprio 1
	s_waitcnt lgkmcnt(0)
	v_mfma_f32_16x16x32_bf16 v[60:63], v[148:151], v[208:211], v[60:63]
	v_mfma_f32_16x16x32_bf16 v[56:59], v[162:165], v[208:211], v[56:59]
	v_mfma_f32_16x16x32_bf16 v[44:47], v[148:151], v[216:219], v[44:47]
	v_mfma_f32_16x16x32_bf16 v[40:43], v[162:165], v[216:219], v[40:43]
	v_mfma_f32_16x16x32_bf16 v[28:31], v[148:151], v[224:227], v[28:31]
	v_mfma_f32_16x16x32_bf16 v[24:27], v[162:165], v[224:227], v[24:27]
	v_mfma_f32_16x16x32_bf16 v[12:15], v[148:151], v[232:235], v[12:15]
	v_mfma_f32_16x16x32_bf16 v[8:11], v[162:165], v[232:235], v[8:11]
	v_mfma_f32_16x16x32_bf16 v[60:63], v[158:161], v[212:215], v[60:63]
	v_mfma_f32_16x16x32_bf16 v[56:59], v[188:191], v[212:215], v[56:59]
	v_mfma_f32_16x16x32_bf16 v[44:47], v[158:161], v[220:223], v[44:47]
	v_mfma_f32_16x16x32_bf16 v[40:43], v[188:191], v[220:223], v[40:43]
	v_mfma_f32_16x16x32_bf16 v[28:31], v[158:161], v[228:231], v[28:31]
	v_mfma_f32_16x16x32_bf16 v[24:27], v[188:191], v[228:231], v[24:27]
	v_mfma_f32_16x16x32_bf16 v[12:15], v[158:161], v[236:239], v[12:15]
	v_mfma_f32_16x16x32_bf16 v[8:11], v[188:191], v[236:239], v[8:11]
	s_setprio 0
	s_setprio 1
	v_mfma_f32_16x16x32_bf16 v[52:55], v[192:195], v[208:211], v[52:55]
	v_mfma_f32_16x16x32_bf16 v[48:51], v[200:203], v[208:211], v[48:51]
	v_mfma_f32_16x16x32_bf16 v[36:39], v[192:195], v[216:219], v[36:39]
	v_mfma_f32_16x16x32_bf16 v[32:35], v[200:203], v[216:219], v[32:35]
	v_mfma_f32_16x16x32_bf16 v[20:23], v[192:195], v[224:227], v[20:23]
	v_mfma_f32_16x16x32_bf16 v[16:19], v[200:203], v[224:227], v[16:19]
	v_mfma_f32_16x16x32_bf16 v[4:7], v[192:195], v[232:235], v[4:7]
	v_mfma_f32_16x16x32_bf16 v[0:3], v[200:203], v[232:235], v[0:3]
	v_mfma_f32_16x16x32_bf16 v[52:55], v[196:199], v[212:215], v[52:55]
	v_mfma_f32_16x16x32_bf16 v[48:51], v[204:207], v[212:215], v[48:51]
	v_mfma_f32_16x16x32_bf16 v[36:39], v[196:199], v[220:223], v[36:39]
	v_mfma_f32_16x16x32_bf16 v[32:35], v[204:207], v[220:223], v[32:35]
	v_mfma_f32_16x16x32_bf16 v[20:23], v[196:199], v[228:231], v[20:23]
	v_mfma_f32_16x16x32_bf16 v[16:19], v[204:207], v[228:231], v[16:19]
	v_mfma_f32_16x16x32_bf16 v[4:7], v[196:199], v[236:239], v[4:7]
	v_mfma_f32_16x16x32_bf16 v[0:3], v[204:207], v[236:239], v[0:3]
	s_setprio 0
	s_barrier
	s_add_i32 s31, s31, 2
	s_add_u32 s8, s8, 0x100
	s_addc_u32 s9, s9, 0
	s_add_u32 s29, s29, 0x100
	s_addc_u32 s30, s30, 0
	s_cmp_gt_u32 s31, 13
	s_cbranch_scc0 .LBB0_35
	s_and_b64 vcc, exec, s[10:11]
	s_cbranch_vccz .LBB0_38
	s_barrier
.LBB0_38:
	s_lshl_b32 s13, s25, 8
	s_add_i32 s13, s13, s75
	v_or_b32_e32 v150, s13, v153
	s_andn2_b64 vcc, exec, s[66:67]
	s_cbranch_vccnz .Lupepi_nors
	v_lshlrev_b32_e32 v128, 2, v150
	global_load_dword v200, v128, s[82:83]
	global_load_dword v202, v128, s[82:83] offset:64
	global_load_dword v204, v128, s[82:83] offset:128
	global_load_dword v206, v128, s[82:83] offset:192
	global_load_dword v208, v128, s[82:83] offset:512
	global_load_dword v210, v128, s[82:83] offset:576
	global_load_dword v212, v128, s[82:83] offset:640
	global_load_dword v214, v128, s[82:83] offset:704
	s_branch .Lupepi_go
.Lupepi_nors:
	v_mov_b32_e32 v200, 1.0
	v_mov_b32_e32 v202, 1.0
	v_mov_b32_e32 v204, 1.0
	v_mov_b32_e32 v206, 1.0
	v_mov_b32_e32 v208, 1.0
	v_mov_b32_e32 v210, 1.0
	v_mov_b32_e32 v212, 1.0
	v_mov_b32_e32 v214, 1.0
; __device__ __forceinline__ unsigned cvt_pk_bf16(float lo, float hi) { unsigned r; asm volatile("v_cvt_pk_bf16_f32 %0, %1, %2" : "=v"(r) : "v"(lo), "v"(hi)); return r; }
; __device__ __forceinline__ float relu_sq(float x) { float r; asm volatile("v_max_f32 %0, 0, %1" : "=v"(r) : "v"(x)); return r * r; }
;     __device__ __forceinline__ void operator()(const f32x4 (&acc)[2][2][4][2], const Unit& u, int wr, int wc, int fr, int fq) const {
;         const int row0 = u.pm * BM + wr * 64 + fr; const int col0 = u.pn * BM + wc * 32 + 8 * fq;
; #pragma unroll
;         for (int ai = 0; ai < 2; ++ai)
; #pragma unroll
;             for (int m = 0; m < 4; ++m) { const int row_ = row0 + ai * HALF + m * 16; bf16_t* rowp = O + (size_t)(row_ >> 11) * gs + (size_t)(row_ & 2047) * ldc + col0; const float sc = rs ? rs[row0 + ai * HALF + m * 16] : 1.f;
; #pragma unroll
;                 for (int bj = 0; bj < 2; ++bj) { f32x4 v0 = acc[ai][bj][m][0] * sc, v1 = acc[ai][bj][m][1] * sc;
;                     if (ACT == 1) {
; #pragma unroll
;                         for (int e = 0; e < 4; ++e) { v0[e] = relu_sq(v0[e]); v1[e] = relu_sq(v1[e]); } }
;                     u32x4 w; w.x = cvt_pk_bf16(v0[0], v0[1]); w.y = cvt_pk_bf16(v0[2], v0[3]); w.z = cvt_pk_bf16(v1[0], v1[1]); w.w = cvt_pk_bf16(v1[2], v1[3]);
;                     *(u32x4*)(rowp + bj * HALF) = w; } }
.Lupepi_go:
.LBB0_40:
	s_ashr_i32 s13, s13, 11
	s_mul_hi_i32 s19, s13, 0x1040000
	s_mul_i32 s13, s13, 0x1040000
	v_and_b32_e32 v128, 0x7cf, v150
	s_add_u32 s18, s64, s13
	v_mul_u32_u24_e32 v128, 0x1040, v128
	s_waitcnt vmcnt(0)
	v_pk_mul_f32 v[124:125], v[124:125], v[200:201] op_sel_hi:[1,0]
	v_pk_mul_f32 v[120:121], v[120:121], v[200:201] op_sel_hi:[1,0]
	s_addc_u32 s19, s65, s19
	v_lshlrev_b32_e32 v128, 1, v128
	v_max_f32 v124, 0, v124
	v_max_f32 v120, 0, v120
	v_lshl_add_u64 v[158:159], s[18:19], 0, v[128:129]
	v_pk_mul_f32 v[122:123], v[122:123], v[200:201] op_sel_hi:[1,0]
	v_mul_f32_e32 v128, v120, v120
	v_max_f32 v120, 0, v125
	v_max_f32 v121, 0, v121
	v_lshl_or_b32 v148, s24, 8, v156
	v_pk_mul_f32 v[126:127], v[126:127], v[200:201] op_sel_hi:[1,0]
	v_mul_f32_e32 v125, v121, v121
	v_max_f32 v121, 0, v126
	v_max_f32 v122, 0, v122
	v_ashrrev_i32_e32 v149, 31, v148
	v_mul_f32_e32 v126, v122, v122
	v_max_f32 v122, 0, v127
	v_max_f32 v123, 0, v123
	v_lshl_add_u64 v[158:159], v[148:149], 1, v[158:159]
	v_mul_f32_e32 v120, v120, v120
	v_mul_f32_e32 v121, v121, v121
	v_mul_f32_e32 v122, v122, v122
	v_mul_f32_e32 v123, v123, v123
	v_pk_mul_f32 v[116:117], v[116:117], v[200:201] op_sel_hi:[1,0]
	v_pk_mul_f32 v[112:113], v[112:113], v[200:201] op_sel_hi:[1,0]
	v_mul_f32_e32 v124, v124, v124
	v_cvt_pk_bf16_f32 v120, v124, v120
	v_cvt_pk_bf16_f32 v121, v121, v122
	v_cvt_pk_bf16_f32 v122, v128, v125
	v_cvt_pk_bf16_f32 v123, v126, v123
	global_store_dwordx4 v[158:159], v[120:123], off
	v_max_f32 v116, 0, v116
	v_max_f32 v112, 0, v112
	v_pk_mul_f32 v[114:115], v[114:115], v[200:201] op_sel_hi:[1,0]
	v_pk_mul_f32 v[118:119], v[118:119], v[200:201] op_sel_hi:[1,0]
	v_mul_f32_e32 v120, v112, v112
	v_max_f32 v112, 0, v117
	v_max_f32 v113, 0, v113
	v_mul_f32_e32 v116, v116, v116
	v_mul_f32_e32 v117, v113, v113
	v_max_f32 v113, 0, v118
	v_max_f32 v114, 0, v114
	v_mul_f32_e32 v112, v112, v112
	v_mul_f32_e32 v118, v114, v114
	v_max_f32 v114, 0, v119
	v_max_f32 v115, 0, v115
	v_mul_f32_e32 v113, v113, v113
	v_mul_f32_e32 v114, v114, v114
	v_mul_f32_e32 v115, v115, v115
	v_cvt_pk_bf16_f32 v112, v116, v112
	v_cvt_pk_bf16_f32 v113, v113, v114
	v_cvt_pk_bf16_f32 v114, v120, v117
	v_cvt_pk_bf16_f32 v115, v118, v115
	global_store_dwordx4 v[158:159], v[112:115], off offset:256
	s_nop 0
	s_nop 0
	v_or_b32_e32 v112, 16, v150
	s_nop 0
.LBB0_42:
	s_nop 0
	v_pk_mul_f32 v[108:109], v[108:109], v[202:203] op_sel_hi:[1,0]
	v_pk_mul_f32 v[104:105], v[104:105], v[202:203] op_sel_hi:[1,0]
	v_and_b32_e32 v112, 0x7df, v112
	v_max_f32 v108, 0, v108
	v_max_f32 v104, 0, v104
	v_mul_u32_u24_e32 v112, 0x1040, v112
	v_pk_mul_f32 v[106:107], v[106:107], v[202:203] op_sel_hi:[1,0]
	v_mul_f32_e32 v114, v104, v104
	v_max_f32 v104, 0, v109
	v_max_f32 v105, 0, v105
	v_lshlrev_b32_e32 v128, 1, v112
	v_pk_mul_f32 v[110:111], v[110:111], v[202:203] op_sel_hi:[1,0]
	v_mul_f32_e32 v109, v105, v105
	v_max_f32 v105, 0, v110
	v_max_f32 v106, 0, v106
	v_lshl_add_u64 v[112:113], s[18:19], 0, v[128:129]
	v_mul_f32_e32 v110, v106, v106
	v_max_f32 v106, 0, v111
	v_max_f32 v107, 0, v107
	v_lshl_add_u64 v[112:113], v[148:149], 1, v[112:113]
	v_mul_f32_e32 v104, v104, v104
	v_mul_f32_e32 v105, v105, v105
	v_mul_f32_e32 v106, v106, v106
	v_mul_f32_e32 v107, v107, v107
	v_pk_mul_f32 v[100:101], v[100:101], v[202:203] op_sel_hi:[1,0]
	v_pk_mul_f32 v[96:97], v[96:97], v[202:203] op_sel_hi:[1,0]
	v_mul_f32_e32 v108, v108, v108
	v_cvt_pk_bf16_f32 v104, v108, v104
	v_cvt_pk_bf16_f32 v105, v105, v106
	v_cvt_pk_bf16_f32 v106, v114, v109
	v_cvt_pk_bf16_f32 v107, v110, v107
	global_store_dwordx4 v[112:113], v[104:107], off
	v_max_f32 v100, 0, v100
	v_max_f32 v96, 0, v96
	v_pk_mul_f32 v[98:99], v[98:99], v[202:203] op_sel_hi:[1,0]
	v_pk_mul_f32 v[102:103], v[102:103], v[202:203] op_sel_hi:[1,0]
	v_mul_f32_e32 v104, v96, v96
	v_max_f32 v96, 0, v101
	v_max_f32 v97, 0, v97
	v_mul_f32_e32 v100, v100, v100
	v_mul_f32_e32 v101, v97, v97
	v_max_f32 v97, 0, v102
	v_max_f32 v98, 0, v98
	v_mul_f32_e32 v96, v96, v96
	v_mul_f32_e32 v102, v98, v98
	v_max_f32 v98, 0, v103
	v_mul_f32_e32 v97, v97, v97
	v_mul_f32_e32 v98, v98, v98
	v_max_f32 v99, 0, v99
	v_cvt_pk_bf16_f32 v96, v100, v96
	v_cvt_pk_bf16_f32 v97, v97, v98
	v_cvt_pk_bf16_f32 v98, v104, v101
	v_or_b32_e32 v100, 32, v150
	v_mul_f32_e32 v99, v99, v99
	v_cvt_pk_bf16_f32 v99, v102, v99
	global_store_dwordx4 v[112:113], v[96:99], off offset:256
	s_nop 0
	s_nop 0
	s_nop 0
	s_nop 0
	s_nop 0
.LBB0_44:
	v_and_b32_e32 v97, 0x7ef, v100
	s_nop 0
	v_pk_mul_f32 v[92:93], v[92:93], v[204:205] op_sel_hi:[1,0]
	v_pk_mul_f32 v[88:89], v[88:89], v[204:205] op_sel_hi:[1,0]
	v_mul_u32_u24_e32 v97, 0x1040, v97
	v_max_f32 v92, 0, v92
	v_max_f32 v88, 0, v88
	v_lshlrev_b32_e32 v128, 1, v97
	v_pk_mul_f32 v[90:91], v[90:91], v[204:205] op_sel_hi:[1,0]
	v_mul_f32_e32 v97, v88, v88
	v_max_f32 v88, 0, v93
	v_max_f32 v89, 0, v89
	v_pk_mul_f32 v[94:95], v[94:95], v[204:205] op_sel_hi:[1,0]
	v_mul_f32_e32 v93, v89, v89
	v_max_f32 v89, 0, v94
	v_max_f32 v90, 0, v90
	v_lshl_add_u64 v[100:101], s[18:19], 0, v[128:129]
	v_mul_f32_e32 v94, v90, v90
	v_max_f32 v90, 0, v95
	v_max_f32 v91, 0, v91
	v_lshl_add_u64 v[100:101], v[148:149], 1, v[100:101]
	v_mul_f32_e32 v88, v88, v88
	v_mul_f32_e32 v89, v89, v89
	v_mul_f32_e32 v90, v90, v90
	v_mul_f32_e32 v91, v91, v91
	v_pk_mul_f32 v[84:85], v[84:85], v[204:205] op_sel_hi:[1,0]
	v_pk_mul_f32 v[80:81], v[80:81], v[204:205] op_sel_hi:[1,0]
	v_mul_f32_e32 v92, v92, v92
	v_cvt_pk_bf16_f32 v88, v92, v88
	v_cvt_pk_bf16_f32 v89, v89, v90
	v_cvt_pk_bf16_f32 v90, v97, v93
	v_cvt_pk_bf16_f32 v91, v94, v91
	global_store_dwordx4 v[100:101], v[88:91], off
	v_max_f32 v84, 0, v84
	v_max_f32 v80, 0, v80
	v_pk_mul_f32 v[82:83], v[82:83], v[204:205] op_sel_hi:[1,0]
	v_pk_mul_f32 v[86:87], v[86:87], v[204:205] op_sel_hi:[1,0]
	v_mul_f32_e32 v88, v80, v80
	v_max_f32 v80, 0, v85
	v_max_f32 v81, 0, v81
	v_mul_f32_e32 v84, v84, v84
	v_mul_f32_e32 v85, v81, v81
	v_max_f32 v81, 0, v86
	v_max_f32 v82, 0, v82
	v_mul_f32_e32 v80, v80, v80
	v_mul_f32_e32 v86, v82, v82
	v_max_f32 v82, 0, v87
	v_max_f32 v83, 0, v83
	v_mul_f32_e32 v81, v81, v81
	v_mul_f32_e32 v82, v82, v82
	v_mul_f32_e32 v83, v83, v83
	v_cvt_pk_bf16_f32 v80, v84, v80
	v_cvt_pk_bf16_f32 v81, v81, v82
	v_cvt_pk_bf16_f32 v82, v88, v85
	v_cvt_pk_bf16_f32 v83, v86, v83
	global_store_dwordx4 v[100:101], v[80:83], off offset:256
	s_nop 0
	s_nop 0
	v_or_b32_e32 v80, 48, v150
	s_nop 0
; __device__ __forceinline__ unsigned cvt_pk_bf16(float lo, float hi) { unsigned r; asm volatile("v_cvt_pk_bf16_f32 %0, %1, %2" : "=v"(r) : "v"(lo), "v"(hi)); return r; }
; __device__ __forceinline__ float relu_sq(float x) { float r; asm volatile("v_max_f32 %0, 0, %1" : "=v"(r) : "v"(x)); return r * r; }
;     __device__ __forceinline__ void operator()(const f32x4 (&acc)[2][2][4][2], const Unit& u, int wr, int wc, int fr, int fq) const {
;         const int row0 = u.pm * BM + wr * 64 + fr; const int col0 = u.pn * BM + wc * 32 + 8 * fq;
; #pragma unroll
;         for (int ai = 0; ai < 2; ++ai)
; #pragma unroll
;             for (int m = 0; m < 4; ++m) { const int row_ = row0 + ai * HALF + m * 16; bf16_t* rowp = O + (size_t)(row_ >> 11) * gs + (size_t)(row_ & 2047) * ldc + col0; const float sc = rs ? rs[row0 + ai * HALF + m * 16] : 1.f;
; #pragma unroll
;                 for (int bj = 0; bj < 2; ++bj) { f32x4 v0 = acc[ai][bj][m][0] * sc, v1 = acc[ai][bj][m][1] * sc;
;                     if (ACT == 1) {
; #pragma unroll
;                         for (int e = 0; e < 4; ++e) { v0[e] = relu_sq(v0[e]); v1[e] = relu_sq(v1[e]); } }
;                     u32x4 w; w.x = cvt_pk_bf16(v0[0], v0[1]); w.y = cvt_pk_bf16(v0[2], v0[3]); w.z = cvt_pk_bf16(v1[0], v1[1]); w.w = cvt_pk_bf16(v1[2], v1[3]);
;                     *(u32x4*)(rowp + bj * HALF) = w; } }
.LBB0_46:
	s_nop 0
	v_pk_mul_f32 v[76:77], v[76:77], v[206:207] op_sel_hi:[1,0]
	v_pk_mul_f32 v[72:73], v[72:73], v[206:207] op_sel_hi:[1,0]
	v_and_b32_e32 v80, 0x7ff, v80
	v_max_f32 v76, 0, v76
	v_max_f32 v72, 0, v72
	v_mul_u32_u24_e32 v80, 0x1040, v80
	v_pk_mul_f32 v[74:75], v[74:75], v[206:207] op_sel_hi:[1,0]
	v_mul_f32_e32 v82, v72, v72
	v_max_f32 v72, 0, v77
	v_max_f32 v73, 0, v73
	v_lshlrev_b32_e32 v128, 1, v80
	v_pk_mul_f32 v[78:79], v[78:79], v[206:207] op_sel_hi:[1,0]
	v_mul_f32_e32 v77, v73, v73
	v_max_f32 v73, 0, v78
	v_max_f32 v74, 0, v74
	v_lshl_add_u64 v[80:81], s[18:19], 0, v[128:129]
	v_mul_f32_e32 v78, v74, v74
	v_max_f32 v74, 0, v79
	v_max_f32 v75, 0, v75
	v_lshl_add_u64 v[80:81], v[148:149], 1, v[80:81]
	v_mul_f32_e32 v72, v72, v72
	v_mul_f32_e32 v73, v73, v73
	v_mul_f32_e32 v74, v74, v74
	v_mul_f32_e32 v75, v75, v75
	v_pk_mul_f32 v[68:69], v[68:69], v[206:207] op_sel_hi:[1,0]
	v_pk_mul_f32 v[64:65], v[64:65], v[206:207] op_sel_hi:[1,0]
	v_mul_f32_e32 v76, v76, v76
	v_cvt_pk_bf16_f32 v72, v76, v72
	v_cvt_pk_bf16_f32 v73, v73, v74
	v_cvt_pk_bf16_f32 v74, v82, v77
	v_cvt_pk_bf16_f32 v75, v78, v75
	global_store_dwordx4 v[80:81], v[72:75], off
	v_max_f32 v68, 0, v68
	v_max_f32 v64, 0, v64
	v_pk_mul_f32 v[66:67], v[66:67], v[206:207] op_sel_hi:[1,0]
	v_pk_mul_f32 v[70:71], v[70:71], v[206:207] op_sel_hi:[1,0]
	v_mul_f32_e32 v72, v64, v64
	v_max_f32 v64, 0, v69
	v_max_f32 v65, 0, v65
	v_mul_f32_e32 v68, v68, v68
	v_mul_f32_e32 v69, v65, v65
	v_max_f32 v65, 0, v70
	v_max_f32 v66, 0, v66
	v_mul_f32_e32 v64, v64, v64
	v_mul_f32_e32 v70, v66, v66
	v_max_f32 v66, 0, v71
	v_mul_f32_e32 v65, v65, v65
	v_mul_f32_e32 v66, v66, v66
	v_max_f32 v67, 0, v67
	v_cvt_pk_bf16_f32 v64, v68, v64
	v_cvt_pk_bf16_f32 v65, v65, v66
	v_cvt_pk_bf16_f32 v66, v72, v69
	s_nop 0
	v_mul_f32_e32 v67, v67, v67
	v_cvt_pk_bf16_f32 v67, v70, v67
	global_store_dwordx4 v[80:81], v[64:67], off offset:256
	v_add_u32_e32 v70, 0x80, v150
	s_nop 0
	s_nop 0
	s_nop 0
.LBB0_48:
	v_ashrrev_i32_e32 v67, 11, v70
	v_mov_b64_e32 v[64:65], s[64:65]
	s_mov_b32 s13, 0x1040000
	v_mad_i64_i32 v[64:65], s[18:19], v67, s13, v[64:65]
	v_and_b32_e32 v67, 0x7cf, v70
	s_nop 0
	v_pk_mul_f32 v[60:61], v[60:61], v[208:209] op_sel_hi:[1,0]
	v_pk_mul_f32 v[56:57], v[56:57], v[208:209] op_sel_hi:[1,0]
	v_mul_u32_u24_e32 v67, 0x1040, v67
	v_max_f32 v60, 0, v60
	v_max_f32 v56, 0, v56
	v_lshlrev_b32_e32 v128, 1, v67
	v_pk_mul_f32 v[58:59], v[58:59], v[208:209] op_sel_hi:[1,0]
	v_mul_f32_e32 v67, v56, v56
	v_max_f32 v56, 0, v61
	v_max_f32 v57, 0, v57
	v_pk_mul_f32 v[62:63], v[62:63], v[208:209] op_sel_hi:[1,0]
	v_mul_f32_e32 v61, v57, v57
	v_max_f32 v57, 0, v62
	v_max_f32 v58, 0, v58
	v_lshl_add_u64 v[70:71], v[64:65], 0, v[128:129]
	v_mul_f32_e32 v62, v58, v58
	v_max_f32 v58, 0, v63
	v_max_f32 v59, 0, v59
	v_lshl_add_u64 v[70:71], v[148:149], 1, v[70:71]
	v_mul_f32_e32 v56, v56, v56
	v_mul_f32_e32 v57, v57, v57
	v_mul_f32_e32 v58, v58, v58
	v_mul_f32_e32 v59, v59, v59
	v_pk_mul_f32 v[52:53], v[52:53], v[208:209] op_sel_hi:[1,0]
	v_pk_mul_f32 v[48:49], v[48:49], v[208:209] op_sel_hi:[1,0]
	v_mul_f32_e32 v60, v60, v60
	v_cvt_pk_bf16_f32 v56, v60, v56
	v_cvt_pk_bf16_f32 v57, v57, v58
	v_cvt_pk_bf16_f32 v58, v67, v61
	v_cvt_pk_bf16_f32 v59, v62, v59
	global_store_dwordx4 v[70:71], v[56:59], off
	v_max_f32 v52, 0, v52
	v_max_f32 v48, 0, v48
	v_pk_mul_f32 v[50:51], v[50:51], v[208:209] op_sel_hi:[1,0]
	v_pk_mul_f32 v[54:55], v[54:55], v[208:209] op_sel_hi:[1,0]
	v_mul_f32_e32 v56, v48, v48
	v_max_f32 v48, 0, v53
	v_max_f32 v49, 0, v49
	v_mul_f32_e32 v52, v52, v52
	v_mul_f32_e32 v53, v49, v49
	v_max_f32 v49, 0, v54
	v_max_f32 v50, 0, v50
	v_mul_f32_e32 v48, v48, v48
	v_mul_f32_e32 v54, v50, v50
	v_max_f32 v50, 0, v55
	v_max_f32 v51, 0, v51
	v_mul_f32_e32 v49, v49, v49
	v_mul_f32_e32 v50, v50, v50
	v_mul_f32_e32 v51, v51, v51
	v_cvt_pk_bf16_f32 v48, v52, v48
	v_cvt_pk_bf16_f32 v49, v49, v50
	v_cvt_pk_bf16_f32 v50, v56, v53
	v_cvt_pk_bf16_f32 v51, v54, v51
	global_store_dwordx4 v[70:71], v[48:51], off offset:256
	s_nop 0
	s_nop 0
	v_add_u32_e32 v48, 0x90, v150
	s_nop 0
; __device__ __forceinline__ unsigned cvt_pk_bf16(float lo, float hi) { unsigned r; asm volatile("v_cvt_pk_bf16_f32 %0, %1, %2" : "=v"(r) : "v"(lo), "v"(hi)); return r; }
; __device__ __forceinline__ float relu_sq(float x) { float r; asm volatile("v_max_f32 %0, 0, %1" : "=v"(r) : "v"(x)); return r * r; }
;     __device__ __forceinline__ void operator()(const f32x4 (&acc)[2][2][4][2], const Unit& u, int wr, int wc, int fr, int fq) const {
;         const int row0 = u.pm * BM + wr * 64 + fr; const int col0 = u.pn * BM + wc * 32 + 8 * fq;
; #pragma unroll
;         for (int ai = 0; ai < 2; ++ai)
; #pragma unroll
;             for (int m = 0; m < 4; ++m) { const int row_ = row0 + ai * HALF + m * 16; bf16_t* rowp = O + (size_t)(row_ >> 11) * gs + (size_t)(row_ & 2047) * ldc + col0; const float sc = rs ? rs[row0 + ai * HALF + m * 16] : 1.f;
; #pragma unroll
;                 for (int bj = 0; bj < 2; ++bj) { f32x4 v0 = acc[ai][bj][m][0] * sc, v1 = acc[ai][bj][m][1] * sc;
;                     if (ACT == 1) {
; #pragma unroll
;                         for (int e = 0; e < 4; ++e) { v0[e] = relu_sq(v0[e]); v1[e] = relu_sq(v1[e]); } }
;                     u32x4 w; w.x = cvt_pk_bf16(v0[0], v0[1]); w.y = cvt_pk_bf16(v0[2], v0[3]); w.z = cvt_pk_bf16(v1[0], v1[1]); w.w = cvt_pk_bf16(v1[2], v1[3]);
;                     *(u32x4*)(rowp + bj * HALF) = w; } }
; template <class Epi, class Sched, bool ALIGN_EPI = false, bool SP2 = false>
; __device__ __forceinline__ void gemm_phase(PG8_LAS unsigned char* lds, const Gemm g, const Sched& S, const Epi& E, const int tid) {
;     ...
;         if constexpr (!Epi::AFTER_DRAIN) { E(acc, cur, wr, wc, fr, fq); S.done(cur); }
;         if (!has_next) break;
.LBB0_50:
	s_nop 0
	v_pk_mul_f32 v[44:45], v[44:45], v[210:211] op_sel_hi:[1,0]
	v_pk_mul_f32 v[40:41], v[40:41], v[210:211] op_sel_hi:[1,0]
	v_and_b32_e32 v48, 0x7df, v48
	v_max_f32 v44, 0, v44
	v_max_f32 v40, 0, v40
	v_mul_u32_u24_e32 v48, 0x1040, v48
	v_pk_mul_f32 v[42:43], v[42:43], v[210:211] op_sel_hi:[1,0]
	v_mul_f32_e32 v50, v40, v40
	v_max_f32 v40, 0, v45
	v_max_f32 v41, 0, v41
	v_lshlrev_b32_e32 v128, 1, v48
	v_pk_mul_f32 v[46:47], v[46:47], v[210:211] op_sel_hi:[1,0]
	v_mul_f32_e32 v45, v41, v41
	v_max_f32 v41, 0, v46
	v_max_f32 v42, 0, v42
	v_lshl_add_u64 v[48:49], v[64:65], 0, v[128:129]
	v_mul_f32_e32 v46, v42, v42
	v_max_f32 v42, 0, v47
	v_max_f32 v43, 0, v43
	v_lshl_add_u64 v[48:49], v[148:149], 1, v[48:49]
	v_mul_f32_e32 v40, v40, v40
	v_mul_f32_e32 v41, v41, v41
	v_mul_f32_e32 v42, v42, v42
	v_mul_f32_e32 v43, v43, v43
	v_pk_mul_f32 v[36:37], v[36:37], v[210:211] op_sel_hi:[1,0]
	v_pk_mul_f32 v[32:33], v[32:33], v[210:211] op_sel_hi:[1,0]
	v_mul_f32_e32 v44, v44, v44
	v_cvt_pk_bf16_f32 v40, v44, v40
	v_cvt_pk_bf16_f32 v41, v41, v42
	v_cvt_pk_bf16_f32 v42, v50, v45
	v_cvt_pk_bf16_f32 v43, v46, v43
	global_store_dwordx4 v[48:49], v[40:43], off
	v_max_f32 v36, 0, v36
	v_max_f32 v32, 0, v32
	v_pk_mul_f32 v[34:35], v[34:35], v[210:211] op_sel_hi:[1,0]
	v_pk_mul_f32 v[38:39], v[38:39], v[210:211] op_sel_hi:[1,0]
	v_mul_f32_e32 v40, v32, v32
	v_max_f32 v32, 0, v37
	v_max_f32 v33, 0, v33
	v_mul_f32_e32 v36, v36, v36
	v_mul_f32_e32 v37, v33, v33
	v_max_f32 v33, 0, v38
	v_max_f32 v34, 0, v34
	v_mul_f32_e32 v32, v32, v32
	v_mul_f32_e32 v38, v34, v34
	v_max_f32 v34, 0, v39
	v_mul_f32_e32 v33, v33, v33
	v_mul_f32_e32 v34, v34, v34
	v_max_f32 v35, 0, v35
	v_cvt_pk_bf16_f32 v32, v36, v32
	v_cvt_pk_bf16_f32 v33, v33, v34
	v_cvt_pk_bf16_f32 v34, v40, v37
	v_add_u32_e32 v36, 0xa0, v150
	v_mul_f32_e32 v35, v35, v35
	v_cvt_pk_bf16_f32 v35, v38, v35
	global_store_dwordx4 v[48:49], v[32:35], off offset:256
	s_nop 0
	s_nop 0
	s_nop 0
	s_nop 0
	s_nop 0
.LBB0_52:
	v_and_b32_e32 v33, 0x7ef, v36
	s_nop 0
	v_pk_mul_f32 v[28:29], v[28:29], v[212:213] op_sel_hi:[1,0]
	v_pk_mul_f32 v[24:25], v[24:25], v[212:213] op_sel_hi:[1,0]
	v_mul_u32_u24_e32 v33, 0x1040, v33
	v_max_f32 v28, 0, v28
	v_max_f32 v24, 0, v24
	v_lshlrev_b32_e32 v128, 1, v33
	v_pk_mul_f32 v[26:27], v[26:27], v[212:213] op_sel_hi:[1,0]
	v_mul_f32_e32 v33, v24, v24
	v_max_f32 v24, 0, v29
	v_max_f32 v25, 0, v25
	v_pk_mul_f32 v[30:31], v[30:31], v[212:213] op_sel_hi:[1,0]
	v_mul_f32_e32 v29, v25, v25
	v_max_f32 v25, 0, v30
	v_max_f32 v26, 0, v26
	v_lshl_add_u64 v[36:37], v[64:65], 0, v[128:129]
	v_mul_f32_e32 v30, v26, v26
	v_max_f32 v26, 0, v31
	v_max_f32 v27, 0, v27
	v_lshl_add_u64 v[36:37], v[148:149], 1, v[36:37]
	v_mul_f32_e32 v24, v24, v24
	v_mul_f32_e32 v25, v25, v25
	v_mul_f32_e32 v26, v26, v26
	v_mul_f32_e32 v27, v27, v27
	v_pk_mul_f32 v[20:21], v[20:21], v[212:213] op_sel_hi:[1,0]
	v_pk_mul_f32 v[16:17], v[16:17], v[212:213] op_sel_hi:[1,0]
	v_mul_f32_e32 v28, v28, v28
	v_cvt_pk_bf16_f32 v24, v28, v24
	v_cvt_pk_bf16_f32 v25, v25, v26
	v_cvt_pk_bf16_f32 v26, v33, v29
	v_cvt_pk_bf16_f32 v27, v30, v27
	global_store_dwordx4 v[36:37], v[24:27], off
	v_max_f32 v20, 0, v20
	v_max_f32 v16, 0, v16
	v_pk_mul_f32 v[18:19], v[18:19], v[212:213] op_sel_hi:[1,0]
	v_pk_mul_f32 v[22:23], v[22:23], v[212:213] op_sel_hi:[1,0]
	v_mul_f32_e32 v24, v16, v16
	v_max_f32 v16, 0, v21
	v_max_f32 v17, 0, v17
	v_mul_f32_e32 v20, v20, v20
	v_mul_f32_e32 v21, v17, v17
	v_max_f32 v17, 0, v22
	v_max_f32 v18, 0, v18
	v_mul_f32_e32 v16, v16, v16
	v_mul_f32_e32 v22, v18, v18
	v_max_f32 v18, 0, v23
	v_max_f32 v19, 0, v19
	v_mul_f32_e32 v17, v17, v17
	v_mul_f32_e32 v18, v18, v18
	v_mul_f32_e32 v19, v19, v19
	v_cvt_pk_bf16_f32 v16, v20, v16
	v_cvt_pk_bf16_f32 v17, v17, v18
	v_cvt_pk_bf16_f32 v18, v24, v21
	v_cvt_pk_bf16_f32 v19, v22, v19
	global_store_dwordx4 v[36:37], v[16:19], off offset:256
	s_nop 0
	s_nop 0
	v_add_u32_e32 v16, 0xb0, v150
	s_nop 0
.LBB0_54:
	s_nop 0
	v_pk_mul_f32 v[12:13], v[12:13], v[214:215] op_sel_hi:[1,0]
	v_pk_mul_f32 v[8:9], v[8:9], v[214:215] op_sel_hi:[1,0]
	v_and_b32_e32 v16, 0x7ff, v16
	v_max_f32 v12, 0, v12
	v_max_f32 v8, 0, v8
	v_mul_u32_u24_e32 v16, 0x1040, v16
	v_pk_mul_f32 v[10:11], v[10:11], v[214:215] op_sel_hi:[1,0]
	v_mul_f32_e32 v18, v8, v8
	v_max_f32 v8, 0, v13
	v_max_f32 v9, 0, v9
	v_lshlrev_b32_e32 v128, 1, v16
	v_pk_mul_f32 v[14:15], v[14:15], v[214:215] op_sel_hi:[1,0]
	v_mul_f32_e32 v13, v9, v9
	v_max_f32 v9, 0, v14
	v_max_f32 v10, 0, v10
	v_lshl_add_u64 v[16:17], v[64:65], 0, v[128:129]
	v_mul_f32_e32 v14, v10, v10
	v_max_f32 v10, 0, v15
	v_max_f32 v11, 0, v11
	v_lshl_add_u64 v[16:17], v[148:149], 1, v[16:17]
	v_mul_f32_e32 v8, v8, v8
	v_mul_f32_e32 v9, v9, v9
	v_mul_f32_e32 v10, v10, v10
	v_mul_f32_e32 v11, v11, v11
	v_pk_mul_f32 v[4:5], v[4:5], v[214:215] op_sel_hi:[1,0]
	v_pk_mul_f32 v[0:1], v[0:1], v[214:215] op_sel_hi:[1,0]
	v_mul_f32_e32 v12, v12, v12
	v_cvt_pk_bf16_f32 v8, v12, v8
	v_cvt_pk_bf16_f32 v9, v9, v10
	v_cvt_pk_bf16_f32 v10, v18, v13
	v_cvt_pk_bf16_f32 v11, v14, v11
	global_store_dwordx4 v[16:17], v[8:11], off
	v_max_f32 v4, 0, v4
	v_max_f32 v0, 0, v0
	v_pk_mul_f32 v[2:3], v[2:3], v[214:215] op_sel_hi:[1,0]
	v_pk_mul_f32 v[6:7], v[6:7], v[214:215] op_sel_hi:[1,0]
	v_mul_f32_e32 v8, v0, v0
	v_max_f32 v0, 0, v5
	v_max_f32 v1, 0, v1
	s_andn2_b64 vcc, exec, s[6:7]
	v_mul_f32_e32 v5, v1, v1
	v_max_f32 v1, 0, v6
	v_max_f32 v2, 0, v2
	v_mul_f32_e32 v0, v0, v0
	v_mul_f32_e32 v6, v2, v2
	v_max_f32 v2, 0, v7
	v_max_f32 v3, 0, v3
	v_mul_f32_e32 v1, v1, v1
	v_mul_f32_e32 v2, v2, v2
	v_mul_f32_e32 v3, v3, v3
	s_mov_b64 s[6:7], -1
	v_mul_f32_e32 v4, v4, v4
	v_cvt_pk_bf16_f32 v0, v4, v0
	v_cvt_pk_bf16_f32 v1, v1, v2
	v_cvt_pk_bf16_f32 v2, v8, v5
	v_cvt_pk_bf16_f32 v3, v6, v3
	global_store_dwordx4 v[16:17], v[0:3], off offset:256
	s_cbranch_vccnz .LBB0_27
	s_andn2_b64 vcc, exec, s[4:5]
	s_cbranch_vccnz .LBB0_26
	s_barrier
	s_branch .LBB0_26

; #define PG8_STAGE(bufoff, gbase, voff) do { _Pragma("unroll") for (int _i = 0; _i < 2; ++_i) \
;         __builtin_amdgcn_global_load_lds((const unsigned*)((const char*)(gbase) + (voff)[_i]), (PG8_LAS unsigned*)(lds + (bufoff) + ldsw + _i * 8192), 16, 0, 0); } while (0)
; #define PG8_LDA(dst, b, h) do { _Pragma("unroll") for (int m = 0; m < 4; ++m) _Pragma("unroll") for (int k = 0; k < 2; ++k) dst[m][k] = *(const PG8_LAS bf16x8*)(lds + PG8_SA(b, h) + aoff + m * 2048 + k * 1024); } while (0)
; #define PG8_LDB(dst, b, h) do { _Pragma("unroll") for (int n = 0; n < 2; ++n) _Pragma("unroll") for (int k = 0; k < 2; ++k) dst[n][k] = *(const PG8_LAS bf16x8*)(lds + PG8_SB(b, h) + boff + n * 2048 + k * 1024); } while (0)
; #define PG8_MMA(ai, bj, At, Bt) do { __builtin_amdgcn_s_setprio(1); _Pragma("unroll") for (int m = 0; m < 4; ++m) _Pragma("unroll") for (int n = 0; n < 2; ++n) _Pragma("unroll") for (int k = 0; k < 2; ++k) \
;         acc[ai][bj][m][n] = __builtin_amdgcn_mfma_f32_16x16x32_bf16(Bt[n][k], At[m][k], acc[ai][bj][m][n], 0, 0, 0); __builtin_amdgcn_s_setprio(0); } while (0)
; #define PG8_WAIT_V(n) asm volatile("s_waitcnt vmcnt(" #n ")" ::: "memory")
; #define PG8_BAR __builtin_amdgcn_s_barrier()
; template <class Epi, class Sched, bool ALIGN_EPI = false, bool SP2 = false>
; __device__ __forceinline__ void gemm_phase(PG8_LAS unsigned char* lds, const Gemm g, const Sched& S, const Epi& E, const int tid) {
;     ...
;         for (int t = 0; t < nt; t += 2) {
;             const bool last = (t == nt - 2);
;             const char* a1 = cA + (size_t)(t + 1) * kstep;
;             const char* a2 = last ? nA : cA + (size_t)(t + 2) * kstep; const char* b2 = last ? nB : cB + (size_t)(t + 2) * kstep;
;             const char* a3 = a2 + kstep; const char* b3 = b2 + kstep;
;             if (last && has_next) S.a_ready(nxt);
;             if constexpr (SP2) {
;             PG8_LDB(B0, 0, 0); PG8_LDB(B1, 0, 1); PG8_SCHED; PG8_LDA(At, 0, 0); PG8_STAGE(PG8_SA(1, 1), a1 + hstepA, voffA);
;             PG8_WAIT_V(8); PG8_WAIT_L(0); PG8_BAR; PG8_MMA(0, 0, At, B0); PG8_MMA(0, 1, At, B1); PG8_BAR; PG8_SCHED;
;             PG8_LDA(At, 0, 1); PG8_STAGE(PG8_SB(0, 0), b2, voffB); PG8_STAGE(PG8_SB(0, 1), b2 + hstepB, voffB); PG8_STAGE(PG8_SA(0, 0), a2, voffA);
;             PG8_WAIT_V(8); PG8_WAIT_L(0); PG8_BAR; PG8_MMA(1, 0, At, B0); PG8_MMA(1, 1, At, B1); PG8_BAR; PG8_SCHED;
.LBB0_468:
	s_add_i32 s47, s46, 2
	s_add_u32 s48, s8, 0x80
	s_addc_u32 s49, s9, 0
	s_add_i32 s50, 0, 0x10000
	s_cmp_eq_u32 s30, s46
	s_cselect_b32 s93, s75, s49
	s_cselect_b32 s92, s74, s48
	v_add_u32_e32 v128, s50, v155
	s_cselect_b32 s49, s42, s45
	s_cselect_b32 s48, s43, s44
	s_cmp_eq_u32 s47, 2
	s_cselect_b32 s99, 1, 0
	s_cmp_eq_u32 s29, 1
	s_cselect_b32 s99, 0, s99
	s_add_i32 s46, 0, 0x14000
	ds_read_b128 v[148:151], v128
	ds_read_b128 v[158:161], v128 offset:1024
	ds_read_b128 v[162:165], v128 offset:2048
	ds_read_b128 v[188:191], v128 offset:3072
	v_add_u32_e32 v128, s46, v155
	ds_read_b128 v[192:195], v128
	ds_read_b128 v[196:199], v128 offset:1024
	ds_read_b128 v[200:203], v128 offset:2048
	ds_read_b128 v[204:207], v128 offset:3072
	v_lshl_add_u64 v[166:167], s[8:9], 0, v[144:145]
	s_add_i32 m0, s72, 0xc000
	ds_read_b128 v[208:211], v157
	ds_read_b128 v[212:215], v157 offset:1024
	ds_read_b128 v[216:219], v157 offset:2048
	ds_read_b128 v[220:223], v157 offset:3072
	ds_read_b128 v[224:227], v157 offset:4096
	ds_read_b128 v[228:231], v157 offset:5120
	ds_read_b128 v[232:235], v157 offset:6144
	ds_read_b128 v[236:239], v157 offset:7168
	global_load_lds_dwordx4 v[166:167], off
	v_lshl_add_u64 v[166:167], s[8:9], 0, v[146:147]
	s_add_i32 m0, s72, 0xe000
	s_nop 0
	global_load_lds_dwordx4 v[166:167], off
	s_cmp_eq_u32 s99, 1
	s_cbranch_scc1 .Lkw_pl_0
	s_waitcnt vmcnt(8)
.Lkw_pl_0:
	s_waitcnt lgkmcnt(0)
	s_barrier
	s_setprio 1
	s_waitcnt lgkmcnt(0)
	v_mfma_f32_16x16x32_bf16 v[124:127], v[148:151], v[208:211], v[124:127]
	v_mfma_f32_16x16x32_bf16 v[120:123], v[162:165], v[208:211], v[120:123]
	v_mfma_f32_16x16x32_bf16 v[108:111], v[148:151], v[216:219], v[108:111]
	v_mfma_f32_16x16x32_bf16 v[104:107], v[162:165], v[216:219], v[104:107]
	v_mfma_f32_16x16x32_bf16 v[92:95], v[148:151], v[224:227], v[92:95]
	v_mfma_f32_16x16x32_bf16 v[88:91], v[162:165], v[224:227], v[88:91]
	v_mfma_f32_16x16x32_bf16 v[76:79], v[148:151], v[232:235], v[76:79]
	v_mfma_f32_16x16x32_bf16 v[72:75], v[162:165], v[232:235], v[72:75]
	v_mfma_f32_16x16x32_bf16 v[124:127], v[158:161], v[212:215], v[124:127]
	v_mfma_f32_16x16x32_bf16 v[120:123], v[188:191], v[212:215], v[120:123]
	v_mfma_f32_16x16x32_bf16 v[108:111], v[158:161], v[220:223], v[108:111]
	v_mfma_f32_16x16x32_bf16 v[104:107], v[188:191], v[220:223], v[104:107]
	v_mfma_f32_16x16x32_bf16 v[92:95], v[158:161], v[228:231], v[92:95]
	v_mfma_f32_16x16x32_bf16 v[88:91], v[188:191], v[228:231], v[88:91]
	v_mfma_f32_16x16x32_bf16 v[76:79], v[158:161], v[236:239], v[76:79]
	v_mfma_f32_16x16x32_bf16 v[72:75], v[188:191], v[236:239], v[72:75]
	s_setprio 0
	s_setprio 1
	v_mfma_f32_16x16x32_bf16 v[116:119], v[192:195], v[208:211], v[116:119]
	v_mfma_f32_16x16x32_bf16 v[112:115], v[200:203], v[208:211], v[112:115]
	v_mfma_f32_16x16x32_bf16 v[100:103], v[192:195], v[216:219], v[100:103]
	v_mfma_f32_16x16x32_bf16 v[96:99], v[200:203], v[216:219], v[96:99]
	v_mfma_f32_16x16x32_bf16 v[84:87], v[192:195], v[224:227], v[84:87]
	v_mfma_f32_16x16x32_bf16 v[80:83], v[200:203], v[224:227], v[80:83]
	v_mfma_f32_16x16x32_bf16 v[68:71], v[192:195], v[232:235], v[68:71]
	v_mfma_f32_16x16x32_bf16 v[64:67], v[200:203], v[232:235], v[64:67]
	v_mfma_f32_16x16x32_bf16 v[116:119], v[196:199], v[212:215], v[116:119]
	v_mfma_f32_16x16x32_bf16 v[112:115], v[204:207], v[212:215], v[112:115]
	v_mfma_f32_16x16x32_bf16 v[100:103], v[196:199], v[220:223], v[100:103]
	v_mfma_f32_16x16x32_bf16 v[96:99], v[204:207], v[220:223], v[96:99]
	v_mfma_f32_16x16x32_bf16 v[84:87], v[196:199], v[228:231], v[84:87]
	v_mfma_f32_16x16x32_bf16 v[80:83], v[204:207], v[228:231], v[80:83]
	v_mfma_f32_16x16x32_bf16 v[68:71], v[196:199], v[236:239], v[68:71]
	v_mfma_f32_16x16x32_bf16 v[64:67], v[204:207], v[236:239], v[64:67]
	s_setprio 0
	s_barrier
	s_add_i32 s50, s50, s81
	v_lshl_add_u64 v[166:167], s[48:49], 0, v[138:139]
	s_mov_b32 m0, s50
	ds_read_b128 v[208:211], v157 offset:16384
	ds_read_b128 v[212:215], v157 offset:17408
	ds_read_b128 v[216:219], v157 offset:18432
	ds_read_b128 v[220:223], v157 offset:19456
	ds_read_b128 v[224:227], v157 offset:20480
	ds_read_b128 v[228:231], v157 offset:21504
	ds_read_b128 v[232:235], v157 offset:22528
	ds_read_b128 v[236:239], v157 offset:23552
	global_load_lds_dwordx4 v[166:167], off
	s_add_i32 m0, s50, 0x2000
	v_lshl_add_u64 v[240:241], s[48:49], 0, v[142:143]
	s_add_u32 s48, s48, s21
	s_addc_u32 s49, s49, 0
	s_add_i32 s46, s46, s81
	global_load_lds_dwordx4 v[240:241], off
	v_lshl_add_u64 v[242:243], s[48:49], 0, v[138:139]
	s_mov_b32 m0, s46
	v_lshl_add_u64 v[244:245], s[48:49], 0, v[142:143]
	global_load_lds_dwordx4 v[242:243], off
	s_add_i32 m0, s46, 0x2000
	v_lshl_add_u64 v[246:247], s[92:93], 0, v[136:137]
	global_load_lds_dwordx4 v[244:245], off
	s_mov_b32 m0, s72
	v_lshl_add_u64 v[248:249], s[92:93], 0, v[140:141]
	global_load_lds_dwordx4 v[246:247], off
	s_mov_b32 m0, s73
	s_nop 0
	global_load_lds_dwordx4 v[248:249], off
	s_cmp_eq_u32 s99, 1
	s_cbranch_scc1 .Lkw_pl_1
	s_waitcnt vmcnt(8)
; #define PG8_STAGE(bufoff, gbase, voff) do { _Pragma("unroll") for (int _i = 0; _i < 2; ++_i) \
;         __builtin_amdgcn_global_load_lds((const unsigned*)((const char*)(gbase) + (voff)[_i]), (PG8_LAS unsigned*)(lds + (bufoff) + ldsw + _i * 8192), 16, 0, 0); } while (0)
; #define PG8_LDA(dst, b, h) do { _Pragma("unroll") for (int m = 0; m < 4; ++m) _Pragma("unroll") for (int k = 0; k < 2; ++k) dst[m][k] = *(const PG8_LAS bf16x8*)(lds + PG8_SA(b, h) + aoff + m * 2048 + k * 1024); } while (0)
; #define PG8_LDB(dst, b, h) do { _Pragma("unroll") for (int n = 0; n < 2; ++n) _Pragma("unroll") for (int k = 0; k < 2; ++k) dst[n][k] = *(const PG8_LAS bf16x8*)(lds + PG8_SB(b, h) + boff + n * 2048 + k * 1024); } while (0)
; #define PG8_MMA(ai, bj, At, Bt) do { __builtin_amdgcn_s_setprio(1); _Pragma("unroll") for (int m = 0; m < 4; ++m) _Pragma("unroll") for (int n = 0; n < 2; ++n) _Pragma("unroll") for (int k = 0; k < 2; ++k) \
;         acc[ai][bj][m][n] = __builtin_amdgcn_mfma_f32_16x16x32_bf16(Bt[n][k], At[m][k], acc[ai][bj][m][n], 0, 0, 0); __builtin_amdgcn_s_setprio(0); } while (0)
; #define PG8_WAIT_V(n) asm volatile("s_waitcnt vmcnt(" #n ")" ::: "memory")
; #define PG8_WAIT_L(n) asm volatile("s_waitcnt lgkmcnt(" #n ")" ::: "memory")
; #define PG8_BAR __builtin_amdgcn_s_barrier()
; #define PG8_SCHED __builtin_amdgcn_sched_barrier(0)
; template <class Epi, class Sched, bool ALIGN_EPI = false, bool SP2 = false>
; __device__ __forceinline__ void gemm_phase(PG8_LAS unsigned char* lds, const Gemm g, const Sched& S, const Epi& E, const int tid) {
;     ...
;             PG8_WAIT_V(8); PG8_WAIT_L(0); PG8_BAR; PG8_MMA(0, 0, At, B0); PG8_MMA(0, 1, At, B1); PG8_BAR; PG8_SCHED;
;             PG8_LDA(At, 0, 1); PG8_STAGE(PG8_SB(0, 0), b2, voffB); PG8_STAGE(PG8_SB(0, 1), b2 + hstepB, voffB); PG8_STAGE(PG8_SA(0, 0), a2, voffA);
;             PG8_WAIT_V(8); PG8_WAIT_L(0); PG8_BAR; PG8_MMA(1, 0, At, B0); PG8_MMA(1, 1, At, B1); PG8_BAR; PG8_SCHED;
;             PG8_LDB(B0, 1, 0); PG8_LDB(B1, 1, 1); PG8_SCHED; PG8_LDA(At, 1, 0); PG8_STAGE(PG8_SA(0, 1), a2 + hstepA, voffA);
;             PG8_WAIT_V(8); PG8_WAIT_L(0); PG8_BAR; PG8_MMA(0, 0, At, B0); PG8_MMA(0, 1, At, B1); PG8_BAR; PG8_SCHED;
.Lkw_pl_1:
	s_waitcnt lgkmcnt(0)
	s_barrier
	s_setprio 1
	s_waitcnt lgkmcnt(0)
	v_mfma_f32_16x16x32_bf16 v[60:63], v[148:151], v[208:211], v[60:63]
	v_mfma_f32_16x16x32_bf16 v[56:59], v[162:165], v[208:211], v[56:59]
	v_mfma_f32_16x16x32_bf16 v[44:47], v[148:151], v[216:219], v[44:47]
	v_mfma_f32_16x16x32_bf16 v[40:43], v[162:165], v[216:219], v[40:43]
	v_mfma_f32_16x16x32_bf16 v[28:31], v[148:151], v[224:227], v[28:31]
	v_mfma_f32_16x16x32_bf16 v[24:27], v[162:165], v[224:227], v[24:27]
	v_mfma_f32_16x16x32_bf16 v[12:15], v[148:151], v[232:235], v[12:15]
	v_mfma_f32_16x16x32_bf16 v[8:11], v[162:165], v[232:235], v[8:11]
	v_mfma_f32_16x16x32_bf16 v[60:63], v[158:161], v[212:215], v[60:63]
	v_mfma_f32_16x16x32_bf16 v[56:59], v[188:191], v[212:215], v[56:59]
	v_mfma_f32_16x16x32_bf16 v[44:47], v[158:161], v[220:223], v[44:47]
	v_mfma_f32_16x16x32_bf16 v[40:43], v[188:191], v[220:223], v[40:43]
	v_mfma_f32_16x16x32_bf16 v[28:31], v[158:161], v[228:231], v[28:31]
	v_mfma_f32_16x16x32_bf16 v[24:27], v[188:191], v[228:231], v[24:27]
	v_mfma_f32_16x16x32_bf16 v[12:15], v[158:161], v[236:239], v[12:15]
	v_mfma_f32_16x16x32_bf16 v[8:11], v[188:191], v[236:239], v[8:11]
	s_setprio 0
	s_setprio 1
	v_mfma_f32_16x16x32_bf16 v[52:55], v[192:195], v[208:211], v[52:55]
	v_mfma_f32_16x16x32_bf16 v[48:51], v[200:203], v[208:211], v[48:51]
	v_mfma_f32_16x16x32_bf16 v[36:39], v[192:195], v[216:219], v[36:39]
	v_mfma_f32_16x16x32_bf16 v[32:35], v[200:203], v[216:219], v[32:35]
	v_mfma_f32_16x16x32_bf16 v[20:23], v[192:195], v[224:227], v[20:23]
	v_mfma_f32_16x16x32_bf16 v[16:19], v[200:203], v[224:227], v[16:19]
	v_mfma_f32_16x16x32_bf16 v[4:7], v[192:195], v[232:235], v[4:7]
	v_mfma_f32_16x16x32_bf16 v[0:3], v[200:203], v[232:235], v[0:3]
	v_mfma_f32_16x16x32_bf16 v[52:55], v[196:199], v[212:215], v[52:55]
	v_mfma_f32_16x16x32_bf16 v[48:51], v[204:207], v[212:215], v[48:51]
	v_mfma_f32_16x16x32_bf16 v[36:39], v[196:199], v[220:223], v[36:39]
	v_mfma_f32_16x16x32_bf16 v[32:35], v[204:207], v[220:223], v[32:35]
	v_mfma_f32_16x16x32_bf16 v[20:23], v[196:199], v[228:231], v[20:23]
	v_mfma_f32_16x16x32_bf16 v[16:19], v[204:207], v[228:231], v[16:19]
	v_mfma_f32_16x16x32_bf16 v[4:7], v[196:199], v[236:239], v[4:7]
	v_mfma_f32_16x16x32_bf16 v[0:3], v[204:207], v[236:239], v[0:3]
	s_setprio 0
	s_barrier
	s_add_i32 s46, 0, 0x18000
	v_add_u32_e32 v128, s46, v155
	s_add_i32 s50, 0, 0x1c000
	ds_read_b128 v[148:151], v128
	ds_read_b128 v[158:161], v128 offset:1024
	ds_read_b128 v[162:165], v128 offset:2048
	ds_read_b128 v[188:191], v128 offset:3072
	v_add_u32_e32 v128, s50, v155
	ds_read_b128 v[192:195], v128
	ds_read_b128 v[196:199], v128 offset:1024
	ds_read_b128 v[200:203], v128 offset:2048
	ds_read_b128 v[204:207], v128 offset:3072
	s_add_u32 s48, s92, s84
	s_addc_u32 s49, s93, 0
	s_mov_b32 m0, s24
	v_lshl_add_u64 v[250:251], s[48:49], 0, v[136:137]
	ds_read_b128 v[208:211], v157 offset:32768
	ds_read_b128 v[212:215], v157 offset:33792
	ds_read_b128 v[216:219], v157 offset:34816
	ds_read_b128 v[220:223], v157 offset:35840
	ds_read_b128 v[224:227], v157 offset:36864
	ds_read_b128 v[228:231], v157 offset:37888
	ds_read_b128 v[232:235], v157 offset:38912
	ds_read_b128 v[236:239], v157 offset:39936
	global_load_lds_dwordx4 v[250:251], off
	v_lshl_add_u64 v[250:251], s[48:49], 0, v[140:141]
	s_mov_b32 m0, s25
	s_nop 0
	global_load_lds_dwordx4 v[250:251], off
	s_waitcnt vmcnt(8)
	s_waitcnt lgkmcnt(0)
	s_barrier
	s_setprio 1
	s_waitcnt lgkmcnt(0)
	v_mfma_f32_16x16x32_bf16 v[124:127], v[148:151], v[208:211], v[124:127]
	v_mfma_f32_16x16x32_bf16 v[120:123], v[162:165], v[208:211], v[120:123]
	v_mfma_f32_16x16x32_bf16 v[108:111], v[148:151], v[216:219], v[108:111]
	v_mfma_f32_16x16x32_bf16 v[104:107], v[162:165], v[216:219], v[104:107]
	v_mfma_f32_16x16x32_bf16 v[92:95], v[148:151], v[224:227], v[92:95]
	v_mfma_f32_16x16x32_bf16 v[88:91], v[162:165], v[224:227], v[88:91]
	v_mfma_f32_16x16x32_bf16 v[76:79], v[148:151], v[232:235], v[76:79]
	v_mfma_f32_16x16x32_bf16 v[72:75], v[162:165], v[232:235], v[72:75]
	v_mfma_f32_16x16x32_bf16 v[124:127], v[158:161], v[212:215], v[124:127]
	v_mfma_f32_16x16x32_bf16 v[120:123], v[188:191], v[212:215], v[120:123]
	v_mfma_f32_16x16x32_bf16 v[108:111], v[158:161], v[220:223], v[108:111]
	v_mfma_f32_16x16x32_bf16 v[104:107], v[188:191], v[220:223], v[104:107]
	v_mfma_f32_16x16x32_bf16 v[92:95], v[158:161], v[228:231], v[92:95]
	v_mfma_f32_16x16x32_bf16 v[88:91], v[188:191], v[228:231], v[88:91]
	v_mfma_f32_16x16x32_bf16 v[76:79], v[158:161], v[236:239], v[76:79]
	v_mfma_f32_16x16x32_bf16 v[72:75], v[188:191], v[236:239], v[72:75]
	s_setprio 0
	s_setprio 1
	v_mfma_f32_16x16x32_bf16 v[116:119], v[192:195], v[208:211], v[116:119]
	v_mfma_f32_16x16x32_bf16 v[112:115], v[200:203], v[208:211], v[112:115]
	v_mfma_f32_16x16x32_bf16 v[100:103], v[192:195], v[216:219], v[100:103]
	v_mfma_f32_16x16x32_bf16 v[96:99], v[200:203], v[216:219], v[96:99]
	v_mfma_f32_16x16x32_bf16 v[84:87], v[192:195], v[224:227], v[84:87]
	v_mfma_f32_16x16x32_bf16 v[80:83], v[200:203], v[224:227], v[80:83]
	v_mfma_f32_16x16x32_bf16 v[68:71], v[192:195], v[232:235], v[68:71]
	v_mfma_f32_16x16x32_bf16 v[64:67], v[200:203], v[232:235], v[64:67]
	v_mfma_f32_16x16x32_bf16 v[116:119], v[196:199], v[212:215], v[116:119]
	v_mfma_f32_16x16x32_bf16 v[112:115], v[204:207], v[212:215], v[112:115]
	v_mfma_f32_16x16x32_bf16 v[100:103], v[196:199], v[220:223], v[100:103]
	v_mfma_f32_16x16x32_bf16 v[96:99], v[204:207], v[220:223], v[96:99]
	v_mfma_f32_16x16x32_bf16 v[84:87], v[196:199], v[228:231], v[84:87]
	v_mfma_f32_16x16x32_bf16 v[80:83], v[204:207], v[228:231], v[80:83]
	v_mfma_f32_16x16x32_bf16 v[68:71], v[196:199], v[236:239], v[68:71]
	v_mfma_f32_16x16x32_bf16 v[64:67], v[204:207], v[236:239], v[64:67]
	s_setprio 0
	s_barrier
; #define PG8_STAGE(bufoff, gbase, voff) do { _Pragma("unroll") for (int _i = 0; _i < 2; ++_i) \
;         __builtin_amdgcn_global_load_lds((const unsigned*)((const char*)(gbase) + (voff)[_i]), (PG8_LAS unsigned*)(lds + (bufoff) + ldsw + _i * 8192), 16, 0, 0); } while (0)
; #define PG8_LDA(dst, b, h) do { _Pragma("unroll") for (int m = 0; m < 4; ++m) _Pragma("unroll") for (int k = 0; k < 2; ++k) dst[m][k] = *(const PG8_LAS bf16x8*)(lds + PG8_SA(b, h) + aoff + m * 2048 + k * 1024); } while (0)
; #define PG8_MMA(ai, bj, At, Bt) do { __builtin_amdgcn_s_setprio(1); _Pragma("unroll") for (int m = 0; m < 4; ++m) _Pragma("unroll") for (int n = 0; n < 2; ++n) _Pragma("unroll") for (int k = 0; k < 2; ++k) \
;         acc[ai][bj][m][n] = __builtin_amdgcn_mfma_f32_16x16x32_bf16(Bt[n][k], At[m][k], acc[ai][bj][m][n], 0, 0, 0); __builtin_amdgcn_s_setprio(0); } while (0)
; #define PG8_WAIT_V(n) asm volatile("s_waitcnt vmcnt(" #n ")" ::: "memory")
; #define PG8_WAIT_L(n) asm volatile("s_waitcnt lgkmcnt(" #n ")" ::: "memory")
; #define PG8_BAR __builtin_amdgcn_s_barrier()
; #define PG8_SCHED __builtin_amdgcn_sched_barrier(0)
;     __device__ __forceinline__ void operator()(const f32x4 (&acc)[2][2][4][2], const Unit& u, int wr, int wc, int fr, int fq) const {
;         const int row0 = u.pm * BM + wr * 64 + fr; const int col0 = u.pn * BM + wc * 32 + 8 * fq;
; #pragma unroll
;         for (int ai = 0; ai < 2; ++ai)
; #pragma unroll
;             for (int m = 0; m < 4; ++m) { const int row_ = row0 + ai * HALF + m * 16; bf16_t* rowp = O + (size_t)(row_ >> 11) * gs + (size_t)(row_ & 2047) * ldc + col0; const float sc = rs ? rs[row0 + ai * HALF + m * 16] : 1.f;
; template <class Epi, class Sched, bool ALIGN_EPI = false, bool SP2 = false>
; __device__ __forceinline__ void gemm_phase(PG8_LAS unsigned char* lds, const Gemm g, const Sched& S, const Epi& E, const int tid) {
;     ...
;             PG8_WAIT_V(8); PG8_WAIT_L(0); PG8_BAR; PG8_MMA(0, 0, At, B0); PG8_MMA(0, 1, At, B1); PG8_BAR; PG8_SCHED;
;             PG8_LDA(At, 1, 1); PG8_STAGE(PG8_SB(1, 0), b3, voffB); PG8_STAGE(PG8_SB(1, 1), b3 + hstepB, voffB); PG8_STAGE(PG8_SA(1, 0), a3, voffA);
;             PG8_WAIT_V(8); PG8_WAIT_L(0); PG8_BAR; PG8_MMA(1, 0, At, B0); PG8_MMA(1, 1, At, B1); PG8_BAR; PG8_SCHED;
	s_add_i32 s46, s46, s81
	v_lshl_add_u64 v[166:167], v[166:167], 0, s[76:77]
	s_mov_b32 m0, s46
	ds_read_b128 v[208:211], v157 offset:49152
	ds_read_b128 v[212:215], v157 offset:50176
	ds_read_b128 v[216:219], v157 offset:51200
	ds_read_b128 v[220:223], v157 offset:52224
	ds_read_b128 v[224:227], v157 offset:53248
	ds_read_b128 v[228:231], v157 offset:54272
	ds_read_b128 v[232:235], v157 offset:55296
	ds_read_b128 v[236:239], v157 offset:56320
	global_load_lds_dwordx4 v[166:167], off
	v_lshl_add_u64 v[166:167], v[240:241], 0, s[76:77]
	s_add_i32 m0, s46, 0x2000
	s_add_i32 s46, s50, s81
	global_load_lds_dwordx4 v[166:167], off
	v_lshl_add_u64 v[166:167], v[242:243], 0, s[76:77]
	s_mov_b32 m0, s46
	s_nop 0
	global_load_lds_dwordx4 v[166:167], off
	v_lshl_add_u64 v[166:167], v[244:245], 0, s[76:77]
	s_add_i32 m0, s46, 0x2000
	s_nop 0
	global_load_lds_dwordx4 v[166:167], off
	v_lshl_add_u64 v[166:167], v[246:247], 0, s[76:77]
	s_mov_b32 m0, s27
	s_nop 0
	global_load_lds_dwordx4 v[166:167], off
	v_lshl_add_u64 v[166:167], v[248:249], 0, s[76:77]
	s_mov_b32 m0, s28
	s_nop 0
	global_load_lds_dwordx4 v[166:167], off
	s_waitcnt vmcnt(8)
	s_waitcnt lgkmcnt(0)
	s_barrier
	s_setprio 1
	s_waitcnt lgkmcnt(0)
	v_mfma_f32_16x16x32_bf16 v[60:63], v[148:151], v[208:211], v[60:63]
	v_mfma_f32_16x16x32_bf16 v[56:59], v[162:165], v[208:211], v[56:59]
	v_mfma_f32_16x16x32_bf16 v[44:47], v[148:151], v[216:219], v[44:47]
	v_mfma_f32_16x16x32_bf16 v[40:43], v[162:165], v[216:219], v[40:43]
	v_mfma_f32_16x16x32_bf16 v[28:31], v[148:151], v[224:227], v[28:31]
	v_mfma_f32_16x16x32_bf16 v[24:27], v[162:165], v[224:227], v[24:27]
	v_mfma_f32_16x16x32_bf16 v[12:15], v[148:151], v[232:235], v[12:15]
	v_mfma_f32_16x16x32_bf16 v[8:11], v[162:165], v[232:235], v[8:11]
	v_mfma_f32_16x16x32_bf16 v[60:63], v[158:161], v[212:215], v[60:63]
	v_mfma_f32_16x16x32_bf16 v[56:59], v[188:191], v[212:215], v[56:59]
	v_mfma_f32_16x16x32_bf16 v[44:47], v[158:161], v[220:223], v[44:47]
	v_mfma_f32_16x16x32_bf16 v[40:43], v[188:191], v[220:223], v[40:43]
	v_mfma_f32_16x16x32_bf16 v[28:31], v[158:161], v[228:231], v[28:31]
	v_mfma_f32_16x16x32_bf16 v[24:27], v[188:191], v[228:231], v[24:27]
	v_mfma_f32_16x16x32_bf16 v[12:15], v[158:161], v[236:239], v[12:15]
	v_mfma_f32_16x16x32_bf16 v[8:11], v[188:191], v[236:239], v[8:11]
	s_setprio 0
	s_setprio 1
	v_mfma_f32_16x16x32_bf16 v[52:55], v[192:195], v[208:211], v[52:55]
	v_mfma_f32_16x16x32_bf16 v[48:51], v[200:203], v[208:211], v[48:51]
	v_mfma_f32_16x16x32_bf16 v[36:39], v[192:195], v[216:219], v[36:39]
	v_mfma_f32_16x16x32_bf16 v[32:35], v[200:203], v[216:219], v[32:35]
	v_mfma_f32_16x16x32_bf16 v[20:23], v[192:195], v[224:227], v[20:23]
	v_mfma_f32_16x16x32_bf16 v[16:19], v[200:203], v[224:227], v[16:19]
	v_mfma_f32_16x16x32_bf16 v[4:7], v[192:195], v[232:235], v[4:7]
	v_mfma_f32_16x16x32_bf16 v[0:3], v[200:203], v[232:235], v[0:3]
	v_mfma_f32_16x16x32_bf16 v[52:55], v[196:199], v[212:215], v[52:55]
	v_mfma_f32_16x16x32_bf16 v[48:51], v[204:207], v[212:215], v[48:51]
	v_mfma_f32_16x16x32_bf16 v[36:39], v[196:199], v[220:223], v[36:39]
	v_mfma_f32_16x16x32_bf16 v[32:35], v[204:207], v[220:223], v[32:35]
	v_mfma_f32_16x16x32_bf16 v[20:23], v[196:199], v[228:231], v[20:23]
	v_mfma_f32_16x16x32_bf16 v[16:19], v[204:207], v[228:231], v[16:19]
	v_mfma_f32_16x16x32_bf16 v[4:7], v[196:199], v[236:239], v[4:7]
	v_mfma_f32_16x16x32_bf16 v[0:3], v[204:207], v[236:239], v[0:3]
	s_setprio 0
	s_barrier
	s_add_u32 s8, s8, 0x100
	s_addc_u32 s9, s9, 0
	s_add_u32 s44, s44, 0x100
	s_addc_u32 s45, s45, 0
	s_cmp_ge_u32 s47, s14
	s_mov_b32 s46, s47
	s_cbranch_scc0 .LBB0_468
	s_and_b64 vcc, exec, s[22:23]
	s_cbranch_vccz .LBB0_471
	s_barrier
.LBB0_471:
	s_lshl_b32 s41, s41, 8
	s_add_i32 s41, s41, s31
	v_or_b32_e32 v150, s41, v153
	s_andn2_b64 vcc, exec, s[68:69]
	s_cbranch_vccnz .Lplepi_nors
	v_lshlrev_b32_e32 v128, 2, v150
	global_load_dword v200, v128, s[82:83]
	global_load_dword v202, v128, s[82:83] offset:64
	global_load_dword v204, v128, s[82:83] offset:128
	global_load_dword v206, v128, s[82:83] offset:192
	global_load_dword v208, v128, s[82:83] offset:512
	global_load_dword v210, v128, s[82:83] offset:576
	global_load_dword v212, v128, s[82:83] offset:640
	global_load_dword v214, v128, s[82:83] offset:704
	s_branch .Lplepi_go

; __device__ __forceinline__ unsigned cvt_pk_bf16(float lo, float hi) { unsigned r; asm volatile("v_cvt_pk_bf16_f32 %0, %1, %2" : "=v"(r) : "v"(lo), "v"(hi)); return r; }
; __device__ __forceinline__ float relu_sq(float x) { float r; asm volatile("v_max_f32 %0, 0, %1" : "=v"(r) : "v"(x)); return r * r; }
;     __device__ __forceinline__ void operator()(const f32x4 (&acc)[2][2][4][2], const Unit& u, int wr, int wc, int fr, int fq) const {
;         const int row0 = u.pm * BM + wr * 64 + fr; const int col0 = u.pn * BM + wc * 32 + 8 * fq;
; #pragma unroll
;         for (int ai = 0; ai < 2; ++ai)
; #pragma unroll
;             for (int m = 0; m < 4; ++m) { const int row_ = row0 + ai * HALF + m * 16; bf16_t* rowp = O + (size_t)(row_ >> 11) * gs + (size_t)(row_ & 2047) * ldc + col0; const float sc = rs ? rs[row0 + ai * HALF + m * 16] : 1.f;
; #pragma unroll
;                 for (int bj = 0; bj < 2; ++bj) { f32x4 v0 = acc[ai][bj][m][0] * sc, v1 = acc[ai][bj][m][1] * sc;
;                     if (ACT == 1) {
; #pragma unroll
;                         for (int e = 0; e < 4; ++e) { v0[e] = relu_sq(v0[e]); v1[e] = relu_sq(v1[e]); } }
;                     u32x4 w; w.x = cvt_pk_bf16(v0[0], v0[1]); w.y = cvt_pk_bf16(v0[2], v0[3]); w.z = cvt_pk_bf16(v1[0], v1[1]); w.w = cvt_pk_bf16(v1[2], v1[3]);
;                     *(u32x4*)(rowp + bj * HALF) = w; } }
.Lplepi_go:
.LBB0_473:
	v_bitop3_b32 v128, s41, v184, v153 bitop3:0xc8
	s_ashr_i32 s41, s41, 11
	s_mul_hi_i32 s43, s26, s41
	s_mul_i32 s42, s26, s41
	s_lshl_b64 s[42:43], s[42:43], 1
	v_lshl_or_b32 v148, s88, 8, v156
	s_add_u32 s88, s12, s42
	v_mul_u32_u24_e32 v128, s39, v128
	s_addc_u32 s89, s13, s43
	v_lshlrev_b32_e32 v128, 1, v128
	v_ashrrev_i32_e32 v149, 31, v148
	v_lshl_add_u64 v[158:159], s[88:89], 0, v[128:129]
	v_lshl_add_u64 v[158:159], v[148:149], 1, v[158:159]
	s_waitcnt vmcnt(0)
	v_pk_mul_f32 v[126:127], v[126:127], v[200:201] op_sel_hi:[1,0]
	v_pk_mul_f32 v[124:125], v[124:125], v[200:201] op_sel_hi:[1,0]
	v_pk_mul_f32 v[160:161], v[122:123], v[200:201] op_sel_hi:[1,0]
	v_pk_mul_f32 v[122:123], v[120:121], v[200:201] op_sel_hi:[1,0]
	v_cvt_pk_bf16_f32 v120, v124, v125
	v_cvt_pk_bf16_f32 v121, v126, v127
	s_nop 0
	v_cvt_pk_bf16_f32 v122, v122, v123
	v_cvt_pk_bf16_f32 v123, v160, v161
	global_store_dwordx4 v[158:159], v[120:123], off
	v_pk_mul_f32 v[118:119], v[118:119], v[200:201] op_sel_hi:[1,0]
	v_pk_mul_f32 v[116:117], v[116:117], v[200:201] op_sel_hi:[1,0]
	v_pk_mul_f32 v[120:121], v[114:115], v[200:201] op_sel_hi:[1,0]
	v_pk_mul_f32 v[114:115], v[112:113], v[200:201] op_sel_hi:[1,0]
	v_cvt_pk_bf16_f32 v112, v116, v117
	v_cvt_pk_bf16_f32 v113, v118, v119
	s_nop 0
	v_cvt_pk_bf16_f32 v114, v114, v115
	v_cvt_pk_bf16_f32 v115, v120, v121
	global_store_dwordx4 v[158:159], v[112:115], off offset:256
	s_nop 0
.LBB0_475:
	s_movk_i32 s41, 0x7df
	v_bitop3_b32 v112, v150, s41, 16 bitop3:0xc8
	v_mul_u32_u24_e32 v112, s39, v112
	v_lshlrev_b32_e32 v128, 1, v112
	v_lshl_add_u64 v[112:113], s[88:89], 0, v[128:129]
	v_lshl_add_u64 v[112:113], v[148:149], 1, v[112:113]
	s_nop 0
	v_pk_mul_f32 v[110:111], v[110:111], v[202:203] op_sel_hi:[1,0]
	v_pk_mul_f32 v[108:109], v[108:109], v[202:203] op_sel_hi:[1,0]
	v_pk_mul_f32 v[114:115], v[106:107], v[202:203] op_sel_hi:[1,0]
	v_pk_mul_f32 v[106:107], v[104:105], v[202:203] op_sel_hi:[1,0]
	v_cvt_pk_bf16_f32 v104, v108, v109
	v_cvt_pk_bf16_f32 v105, v110, v111
	v_pk_mul_f32 v[102:103], v[102:103], v[202:203] op_sel_hi:[1,0]
	v_cvt_pk_bf16_f32 v106, v106, v107
	v_cvt_pk_bf16_f32 v107, v114, v115
	global_store_dwordx4 v[112:113], v[104:107], off
	v_pk_mul_f32 v[100:101], v[100:101], v[202:203] op_sel_hi:[1,0]
	s_nop 0
	v_pk_mul_f32 v[104:105], v[98:99], v[202:203] op_sel_hi:[1,0]
	v_pk_mul_f32 v[98:99], v[96:97], v[202:203] op_sel_hi:[1,0]
	v_cvt_pk_bf16_f32 v96, v100, v101
	v_cvt_pk_bf16_f32 v97, v102, v103
	s_nop 0
	v_cvt_pk_bf16_f32 v98, v98, v99
	v_cvt_pk_bf16_f32 v99, v104, v105
	global_store_dwordx4 v[112:113], v[96:99], off offset:256
	s_nop 1
	s_nop 0
	s_nop 0
	s_nop 0
.LBB0_477:
	v_bitop3_b32 v97, v150, s51, 32 bitop3:0xc8
	v_mul_u32_u24_e32 v97, s39, v97
	v_lshlrev_b32_e32 v128, 1, v97
	v_lshl_add_u64 v[100:101], s[88:89], 0, v[128:129]
	v_lshl_add_u64 v[100:101], v[148:149], 1, v[100:101]
	s_nop 0
	v_pk_mul_f32 v[94:95], v[94:95], v[204:205] op_sel_hi:[1,0]
	v_pk_mul_f32 v[92:93], v[92:93], v[204:205] op_sel_hi:[1,0]
	v_pk_mul_f32 v[102:103], v[90:91], v[204:205] op_sel_hi:[1,0]
	v_pk_mul_f32 v[90:91], v[88:89], v[204:205] op_sel_hi:[1,0]
	v_cvt_pk_bf16_f32 v88, v92, v93
	v_cvt_pk_bf16_f32 v89, v94, v95
	s_nop 0
	v_cvt_pk_bf16_f32 v90, v90, v91
	v_cvt_pk_bf16_f32 v91, v102, v103
	global_store_dwordx4 v[100:101], v[88:91], off
	v_pk_mul_f32 v[86:87], v[86:87], v[204:205] op_sel_hi:[1,0]
	v_pk_mul_f32 v[84:85], v[84:85], v[204:205] op_sel_hi:[1,0]
	v_pk_mul_f32 v[88:89], v[82:83], v[204:205] op_sel_hi:[1,0]
	v_pk_mul_f32 v[82:83], v[80:81], v[204:205] op_sel_hi:[1,0]
	v_cvt_pk_bf16_f32 v80, v84, v85
	v_cvt_pk_bf16_f32 v81, v86, v87
	s_nop 0
	v_cvt_pk_bf16_f32 v82, v82, v83
	v_cvt_pk_bf16_f32 v83, v88, v89
	global_store_dwordx4 v[100:101], v[80:83], off offset:256
	s_nop 0
.LBB0_479:
	s_movk_i32 s41, 0x7ff
	v_bitop3_b32 v80, v150, s41, 48 bitop3:0xc8
	v_mul_u32_u24_e32 v80, s39, v80
	v_lshlrev_b32_e32 v128, 1, v80
	v_lshl_add_u64 v[80:81], s[88:89], 0, v[128:129]
	v_lshl_add_u64 v[80:81], v[148:149], 1, v[80:81]
	s_nop 0
	v_pk_mul_f32 v[78:79], v[78:79], v[206:207] op_sel_hi:[1,0]
	v_pk_mul_f32 v[76:77], v[76:77], v[206:207] op_sel_hi:[1,0]
	v_pk_mul_f32 v[82:83], v[74:75], v[206:207] op_sel_hi:[1,0]
	v_pk_mul_f32 v[74:75], v[72:73], v[206:207] op_sel_hi:[1,0]
	v_cvt_pk_bf16_f32 v72, v76, v77
	v_cvt_pk_bf16_f32 v73, v78, v79
	v_pk_mul_f32 v[70:71], v[70:71], v[206:207] op_sel_hi:[1,0]
	v_cvt_pk_bf16_f32 v74, v74, v75
	v_cvt_pk_bf16_f32 v75, v82, v83
	global_store_dwordx4 v[80:81], v[72:75], off
	v_pk_mul_f32 v[68:69], v[68:69], v[206:207] op_sel_hi:[1,0]
	s_nop 0
	v_pk_mul_f32 v[72:73], v[66:67], v[206:207] op_sel_hi:[1,0]
	v_pk_mul_f32 v[66:67], v[64:65], v[206:207] op_sel_hi:[1,0]
	v_cvt_pk_bf16_f32 v64, v68, v69
	v_cvt_pk_bf16_f32 v65, v70, v71
	s_nop 0
	v_cvt_pk_bf16_f32 v66, v66, v67
	v_cvt_pk_bf16_f32 v67, v72, v73
	global_store_dwordx4 v[80:81], v[64:67], off offset:256
	s_nop 1
	v_add_u32_e32 v64, 0x80, v150
	s_nop 0
	s_nop 0
; __device__ __forceinline__ unsigned cvt_pk_bf16(float lo, float hi) { unsigned r; asm volatile("v_cvt_pk_bf16_f32 %0, %1, %2" : "=v"(r) : "v"(lo), "v"(hi)); return r; }
; __device__ __forceinline__ float relu_sq(float x) { float r; asm volatile("v_max_f32 %0, 0, %1" : "=v"(r) : "v"(x)); return r * r; }
;     __device__ __forceinline__ void operator()(const f32x4 (&acc)[2][2][4][2], const Unit& u, int wr, int wc, int fr, int fq) const {
;         const int row0 = u.pm * BM + wr * 64 + fr; const int col0 = u.pn * BM + wc * 32 + 8 * fq;
; #pragma unroll
;         for (int ai = 0; ai < 2; ++ai)
; #pragma unroll
;             for (int m = 0; m < 4; ++m) { const int row_ = row0 + ai * HALF + m * 16; bf16_t* rowp = O + (size_t)(row_ >> 11) * gs + (size_t)(row_ & 2047) * ldc + col0; const float sc = rs ? rs[row0 + ai * HALF + m * 16] : 1.f;
; #pragma unroll
;                 for (int bj = 0; bj < 2; ++bj) { f32x4 v0 = acc[ai][bj][m][0] * sc, v1 = acc[ai][bj][m][1] * sc;
;                     if (ACT == 1) {
; #pragma unroll
;                         for (int e = 0; e < 4; ++e) { v0[e] = relu_sq(v0[e]); v1[e] = relu_sq(v1[e]); } }
;                     u32x4 w; w.x = cvt_pk_bf16(v0[0], v0[1]); w.y = cvt_pk_bf16(v0[2], v0[3]); w.z = cvt_pk_bf16(v1[0], v1[1]); w.w = cvt_pk_bf16(v1[2], v1[3]);
;                     *(u32x4*)(rowp + bj * HALF) = w; } }
.LBB0_481:
	v_and_b32_e32 v67, 0x7cf, v64
	v_ashrrev_i32_e32 v64, 11, v64
	v_mad_i64_i32 v[64:65], s[42:43], s26, v64, 0
	v_mul_u32_u24_e32 v67, s39, v67
	v_lshl_add_u64 v[64:65], v[64:65], 1, s[12:13]
	v_lshlrev_b32_e32 v128, 1, v67
	v_lshl_add_u64 v[70:71], v[64:65], 0, v[128:129]
	v_lshl_add_u64 v[70:71], v[148:149], 1, v[70:71]
	s_nop 0
	v_pk_mul_f32 v[62:63], v[62:63], v[208:209] op_sel_hi:[1,0]
	v_pk_mul_f32 v[60:61], v[60:61], v[208:209] op_sel_hi:[1,0]
	v_pk_mul_f32 v[72:73], v[58:59], v[208:209] op_sel_hi:[1,0]
	v_pk_mul_f32 v[58:59], v[56:57], v[208:209] op_sel_hi:[1,0]
	v_cvt_pk_bf16_f32 v56, v60, v61
	v_cvt_pk_bf16_f32 v57, v62, v63
	v_pk_mul_f32 v[52:53], v[52:53], v[208:209] op_sel_hi:[1,0]
	v_cvt_pk_bf16_f32 v58, v58, v59
	v_cvt_pk_bf16_f32 v59, v72, v73
	global_store_dwordx4 v[70:71], v[56:59], off
	v_pk_mul_f32 v[54:55], v[54:55], v[208:209] op_sel_hi:[1,0]
	s_nop 0
	v_pk_mul_f32 v[56:57], v[50:51], v[208:209] op_sel_hi:[1,0]
	v_pk_mul_f32 v[50:51], v[48:49], v[208:209] op_sel_hi:[1,0]
	v_cvt_pk_bf16_f32 v48, v52, v53
	v_cvt_pk_bf16_f32 v49, v54, v55
	s_nop 0
	v_cvt_pk_bf16_f32 v50, v50, v51
	v_cvt_pk_bf16_f32 v51, v56, v57
	global_store_dwordx4 v[70:71], v[48:51], off offset:256
	s_nop 1
	v_add_u32_e32 v48, 0x90, v150
	s_nop 0
.LBB0_483:
	v_and_b32_e32 v48, 0x7df, v48
	v_mul_u32_u24_e32 v48, s39, v48
	v_lshlrev_b32_e32 v128, 1, v48
	v_lshl_add_u64 v[48:49], v[64:65], 0, v[128:129]
	v_lshl_add_u64 v[48:49], v[148:149], 1, v[48:49]
	s_nop 0
	v_pk_mul_f32 v[46:47], v[46:47], v[210:211] op_sel_hi:[1,0]
	v_pk_mul_f32 v[44:45], v[44:45], v[210:211] op_sel_hi:[1,0]
	v_pk_mul_f32 v[50:51], v[42:43], v[210:211] op_sel_hi:[1,0]
	v_pk_mul_f32 v[42:43], v[40:41], v[210:211] op_sel_hi:[1,0]
	v_cvt_pk_bf16_f32 v40, v44, v45
	v_cvt_pk_bf16_f32 v41, v46, v47
	v_pk_mul_f32 v[38:39], v[38:39], v[210:211] op_sel_hi:[1,0]
	v_cvt_pk_bf16_f32 v42, v42, v43
	v_cvt_pk_bf16_f32 v43, v50, v51
	global_store_dwordx4 v[48:49], v[40:43], off
	v_pk_mul_f32 v[36:37], v[36:37], v[210:211] op_sel_hi:[1,0]
	s_nop 0
	v_pk_mul_f32 v[40:41], v[34:35], v[210:211] op_sel_hi:[1,0]
	v_pk_mul_f32 v[34:35], v[32:33], v[210:211] op_sel_hi:[1,0]
	v_cvt_pk_bf16_f32 v32, v36, v37
	v_cvt_pk_bf16_f32 v33, v38, v39
	v_add_u32_e32 v36, 0xa0, v150
	v_cvt_pk_bf16_f32 v34, v34, v35
	v_cvt_pk_bf16_f32 v35, v40, v41
	global_store_dwordx4 v[48:49], v[32:35], off offset:256
	s_nop 1
	s_nop 0
	s_nop 0
	s_nop 0
.LBB0_485:
	v_and_b32_e32 v33, 0x7ef, v36
	v_mul_u32_u24_e32 v33, s39, v33
	v_lshlrev_b32_e32 v128, 1, v33
	v_lshl_add_u64 v[36:37], v[64:65], 0, v[128:129]
	v_lshl_add_u64 v[36:37], v[148:149], 1, v[36:37]
	s_nop 0
	v_pk_mul_f32 v[30:31], v[30:31], v[212:213] op_sel_hi:[1,0]
	v_pk_mul_f32 v[28:29], v[28:29], v[212:213] op_sel_hi:[1,0]
	v_pk_mul_f32 v[38:39], v[26:27], v[212:213] op_sel_hi:[1,0]
	v_pk_mul_f32 v[26:27], v[24:25], v[212:213] op_sel_hi:[1,0]
	v_cvt_pk_bf16_f32 v24, v28, v29
	v_cvt_pk_bf16_f32 v25, v30, v31
	v_pk_mul_f32 v[20:21], v[20:21], v[212:213] op_sel_hi:[1,0]
	v_cvt_pk_bf16_f32 v26, v26, v27
	v_cvt_pk_bf16_f32 v27, v38, v39
	global_store_dwordx4 v[36:37], v[24:27], off
	v_pk_mul_f32 v[22:23], v[22:23], v[212:213] op_sel_hi:[1,0]
	s_nop 0
	v_pk_mul_f32 v[24:25], v[18:19], v[212:213] op_sel_hi:[1,0]
	v_pk_mul_f32 v[18:19], v[16:17], v[212:213] op_sel_hi:[1,0]
	v_cvt_pk_bf16_f32 v16, v20, v21
	v_cvt_pk_bf16_f32 v17, v22, v23
	s_nop 0
	v_cvt_pk_bf16_f32 v18, v18, v19
	v_cvt_pk_bf16_f32 v19, v24, v25
	global_store_dwordx4 v[36:37], v[16:19], off offset:256
	s_nop 1
	v_add_u32_e32 v16, 0xb0, v150
	s_nop 0
.LBB0_487:
	v_and_b32_e32 v16, 0x7ff, v16
	v_mul_u32_u24_e32 v16, s39, v16
	v_lshlrev_b32_e32 v128, 1, v16
	v_lshl_add_u64 v[16:17], v[64:65], 0, v[128:129]
	v_lshl_add_u64 v[16:17], v[148:149], 1, v[16:17]
	s_nop 0
	v_pk_mul_f32 v[14:15], v[14:15], v[214:215] op_sel_hi:[1,0]
	v_pk_mul_f32 v[12:13], v[12:13], v[214:215] op_sel_hi:[1,0]
	v_pk_mul_f32 v[18:19], v[10:11], v[214:215] op_sel_hi:[1,0]
	v_pk_mul_f32 v[10:11], v[8:9], v[214:215] op_sel_hi:[1,0]
	v_cvt_pk_bf16_f32 v8, v12, v13
	v_cvt_pk_bf16_f32 v9, v14, v15
	s_and_b64 vcc, exec, s[6:7]
	v_cvt_pk_bf16_f32 v10, v10, v11
	v_cvt_pk_bf16_f32 v11, v18, v19
	global_store_dwordx4 v[16:17], v[8:11], off
	s_mov_b64 s[6:7], -1
	v_pk_mul_f32 v[6:7], v[6:7], v[214:215] op_sel_hi:[1,0]
	v_pk_mul_f32 v[8:9], v[2:3], v[214:215] op_sel_hi:[1,0]
	v_pk_mul_f32 v[2:3], v[0:1], v[214:215] op_sel_hi:[1,0]
	v_pk_mul_f32 v[4:5], v[4:5], v[214:215] op_sel_hi:[1,0]
	s_nop 0
	v_cvt_pk_bf16_f32 v0, v4, v5
	v_cvt_pk_bf16_f32 v1, v6, v7
	v_cvt_pk_bf16_f32 v2, v2, v3
	v_cvt_pk_bf16_f32 v3, v8, v9
	global_store_dwordx4 v[16:17], v[0:3], off offset:256
	s_cbranch_vccnz .LBB0_458
	s_andn2_b64 vcc, exec, s[18:19]
	s_cbranch_vccnz .LBB0_457
	s_barrier
	s_branch .LBB0_457

; __device__ __forceinline__ unsigned xb_ld(unsigned* p)              { return __hip_atomic_load(p, __ATOMIC_RELAXED, __HIP_MEMORY_SCOPE_AGENT); }
; __device__ __forceinline__ unsigned xb_add(unsigned* p, unsigned v) { return __hip_atomic_fetch_add(p, v, __ATOMIC_RELAXED, __HIP_MEMORY_SCOPE_AGENT); }
; #define XB_SPIN(cond, bar) do { unsigned _sp = 0; while (cond) { __builtin_amdgcn_s_sleep(1); \
;     if ((++_sp & 255u) == 0u) { if (xb_ld(&(bar)[XB_TMO])) break; if (_sp > XB_SPIN_CAP) { atomicAdd(&(bar)[XB_TMO], 1u); break; } } } } while (0)
; __device__ __forceinline__ void group_barrier(unsigned* ctl, int x, unsigned target, bool coloc) {
;     asm volatile("s_waitcnt vmcnt(0)" ::: "memory");
;     __syncthreads();
;     if (threadIdx.x == 0) {
;         if (!coloc) { __builtin_amdgcn_fence(__ATOMIC_RELEASE, "agent"); asm volatile("s_waitcnt vmcnt(0)" ::: "memory"); }
;         (void)xb_add(&ctl[GB_CNT(x)], 1u);
;         XB_SPIN(xb_ld(&ctl[GB_CNT(x)]) < target, ctl);
;         __builtin_amdgcn_fence(__ATOMIC_ACQUIRE, "agent");
; __global__ void __launch_bounds__(NWAVES * 64, 2) hybrid_fwd(Args args) {
;     ...
;             else if (local) { unsigned* ctl = (unsigned*)(args.ws + WS_CTL); const int x = blockIdx.x & 7; ++gbn;
;                 const unsigned mk = xb_ld(&ctl[GB_MASK(x)]); group_barrier(ctl, x, 32u * gbn, (mk & (mk - 1u)) == 0u && mk != 0u); }
.LBB0_701:
	s_and_b64 vcc, exec, s[0:1]
	s_mov_b32 s10, s69
	s_cbranch_vccz .LBB0_716
	s_add_i32 s10, s69, 1
	s_cmp_lg_u32 s69, 0
	s_cbranch_scc1 .Lgb_nomask
	v_readlane_b32 s0, v253, 52
	v_readlane_b32 s1, v253, 53
	s_nop 4
	global_load_dword v0, v129, s[0:1] sc1
.Lgb_nomask:
	s_waitcnt vmcnt(0)
	s_barrier
	s_mov_b64 s[0:1], exec
	v_readlane_b32 s4, v253, 0
	v_readlane_b32 s5, v253, 1
	s_and_b64 s[4:5], s[0:1], s[4:5]
	s_mov_b64 exec, s[4:5]
	s_cbranch_execz .LBB0_732
	s_cmp_lg_u32 s69, 0
	s_cbranch_scc1 .Lgb_cached
	s_waitcnt vmcnt(0)
	v_bcnt_u32_b32 v0, v0, 0
	v_cmp_eq_u32_e32 vcc, 1, v0
	s_mov_b32 s98, 1
	s_cbranch_vccnz .LBB0_705
	s_mov_b32 s98, 0
	s_branch .Lgb_wb
.Lgb_cached:
	s_cmp_eq_u32 s98, 1
	s_cbranch_scc1 .LBB0_705
.Lgb_wb:
	buffer_wbl2 sc1
	s_waitcnt vmcnt(0)

; __device__ __forceinline__ unsigned xb_ld(unsigned* p)              { return __hip_atomic_load(p, __ATOMIC_RELAXED, __HIP_MEMORY_SCOPE_AGENT); }
; __device__ __forceinline__ unsigned xb_add(unsigned* p, unsigned v) { return __hip_atomic_fetch_add(p, v, __ATOMIC_RELAXED, __HIP_MEMORY_SCOPE_AGENT); }
; #define XB_SPIN(cond, bar) do { unsigned _sp = 0; while (cond) { __builtin_amdgcn_s_sleep(1); \
;     if ((++_sp & 255u) == 0u) { if (xb_ld(&(bar)[XB_TMO])) break; if (_sp > XB_SPIN_CAP) { atomicAdd(&(bar)[XB_TMO], 1u); break; } } } } while (0)
; __device__ __forceinline__ void group_barrier(unsigned* ctl, int x, unsigned target, bool coloc) {
;     ...
;         (void)xb_add(&ctl[GB_CNT(x)], 1u);
;         XB_SPIN(xb_ld(&ctl[GB_CNT(x)]) < target, ctl);
;         __builtin_amdgcn_fence(__ATOMIC_ACQUIRE, "agent");
;         asm volatile("s_waitcnt vmcnt(0)" ::: "memory");
.LBB0_707:
	s_or_b64 exec, exec, s[4:5]
	buffer_inv sc1
	v_readlane_b32 s4, v253, 54
	v_readlane_b32 s5, v253, 55
	s_lshl_b32 s3, s10, 5
	s_nop 3
	global_load_dword v0, v129, s[4:5] sc1
	s_waitcnt vmcnt(0)
	v_cmp_le_u32_e32 vcc, s3, v0
	s_cbranch_vccnz .LBB0_731
	s_mov_b32 s11, 1
	s_branch .LBB0_710

; __device__ __forceinline__ void group_barrier(unsigned* ctl, int x, unsigned target, bool coloc) {
;     ...
;         __builtin_amdgcn_fence(__ATOMIC_ACQUIRE, "agent");
;         asm volatile("s_waitcnt vmcnt(0)" ::: "memory");
.LBB0_731:
	s_waitcnt vmcnt(0)
	s_waitcnt vmcnt(0)

; #define LAS __attribute__((address_space(3)))
; __global__ void __launch_bounds__(NWAVES * 64, 2) hybrid_fwd(Args args) {
;     extern __shared__ __attribute__((aligned(16))) unsigned char lds_raw[];
;     LAS unsigned char* lds = (LAS unsigned char*)lds_raw;
	.amdhsa_kernel _Z10hybrid_fwd4Args
		.amdhsa_group_segment_fixed_size 0
		.amdhsa_private_segment_fixed_size 0
		.amdhsa_kernarg_size 472
		.amdhsa_user_sgpr_count 2
		.amdhsa_user_sgpr_dispatch_ptr 0
		.amdhsa_user_sgpr_queue_ptr 0
		.amdhsa_user_sgpr_kernarg_segment_ptr 1
		.amdhsa_user_sgpr_dispatch_id 0
		.amdhsa_user_sgpr_kernarg_preload_length 0
		.amdhsa_user_sgpr_kernarg_preload_offset 0
		.amdhsa_user_sgpr_private_segment_size 0
		.amdhsa_uses_dynamic_stack 0
		.amdhsa_enable_private_segment 0
		.amdhsa_system_sgpr_workgroup_id_x 1
		.amdhsa_system_sgpr_workgroup_id_y 0
		.amdhsa_system_sgpr_workgroup_id_z 0
		.amdhsa_system_sgpr_workgroup_info 0
		.amdhsa_system_vgpr_workitem_id 2
		.amdhsa_next_free_vgpr 255
		.amdhsa_next_free_sgpr 100
		.amdhsa_accum_offset 256
		.amdhsa_reserve_vcc 1
		.amdhsa_float_round_mode_32 0
		.amdhsa_float_round_mode_16_64 0
		.amdhsa_float_denorm_mode_32 3
		.amdhsa_float_denorm_mode_16_64 3
		.amdhsa_dx10_clamp 1
		.amdhsa_ieee_mode 1
		.amdhsa_fp16_overflow 0
		.amdhsa_tg_split 0
		.amdhsa_exception_fp_ieee_invalid_op 0
		.amdhsa_exception_fp_denorm_src 0
		.amdhsa_exception_fp_ieee_div_zero 0
		.amdhsa_exception_fp_ieee_overflow 0
		.amdhsa_exception_fp_ieee_underflow 0
		.amdhsa_exception_fp_ieee_inexact 0
		.amdhsa_exception_int_div_zero 0
	.end_amdhsa_kernel

; #define LAS __attribute__((address_space(3)))
; __global__ void __launch_bounds__(NWAVES * 64, 2) hybrid_fwd(Args args) {
;     extern __shared__ __attribute__((aligned(16))) unsigned char lds_raw[];
;     LAS unsigned char* lds = (LAS unsigned char*)lds_raw;
amdhsa.kernels:
  - .agpr_count:     0
    .args:
      - .offset:         0
        .size:           216
        .value_kind:     by_value
      - .offset:         216
        .size:           4
        .value_kind:     hidden_block_count_x
      - .offset:         220
        .size:           4
        .value_kind:     hidden_block_count_y
      - .offset:         224
        .size:           4
        .value_kind:     hidden_block_count_z
      - .offset:         228
        .size:           2
        .value_kind:     hidden_group_size_x
      - .offset:         230
        .size:           2
        .value_kind:     hidden_group_size_y
      - .offset:         232
        .size:           2
        .value_kind:     hidden_group_size_z
      - .offset:         234
        .size:           2
        .value_kind:     hidden_remainder_x
      - .offset:         236
        .size:           2
        .value_kind:     hidden_remainder_y
      - .offset:         238
        .size:           2
        .value_kind:     hidden_remainder_z
      - .offset:         256
        .size:           8
        .value_kind:     hidden_global_offset_x
      - .offset:         264
        .size:           8
        .value_kind:     hidden_global_offset_y
      - .offset:         272
        .size:           8
        .value_kind:     hidden_global_offset_z
      - .offset:         280
        .size:           2
        .value_kind:     hidden_grid_dims
      - .offset:         304
        .size:           8
        .value_kind:     hidden_multigrid_sync_arg
      - .offset:         336
        .size:           4
        .value_kind:     hidden_dynamic_lds_size
    .group_segment_fixed_size: 0
    .kernarg_segment_align: 8
    .kernarg_segment_size: 472
    .language:       OpenCL C
    .language_version:
      - 2
      - 0
    .max_flat_workgroup_size: 512
    .name:           _Z10hybrid_fwd4Args
    .private_segment_fixed_size: 0
    .sgpr_count:     106
    .sgpr_spill_count: 158
    .symbol:         _Z10hybrid_fwd4Args.kd
    .uniform_work_group_size: 1
    .uses_dynamic_stack: false
    .vgpr_count:     255
    .vgpr_spill_count: 0
    .wavefront_size: 64
